# v7 plus cumsum rotating load prefetch, SGU trip-load prefetch, SGU epilogue stores staged through LDS as dwordx4, static prio for waves 0-3 in attention
# speedup vs baseline: 1.0042x; 1.0042x over previous
; __device__ __forceinline__ void ph_misc(const Args& a, char* lds, int l) {
;     ...
;         for (int b = 0; b < NB; ++b) {
;             const int owner = (G >= 256) ? 192 + 8 * b : b % G;
;             if ((int)blockIdx.x != owner) continue;
.LBB0_601:
	s_waitcnt vmcnt(0)
	s_add_i32 s27, s27, 1
	s_mov_b64 s[0:1], 0x8000
	v_lshl_add_u64 v[10:11], v[10:11], 0, s[0:1]
	s_cmp_lg_u32 s27, 8
	v_lshl_add_u64 v[8:9], v[8:9], 0, s[0:1]
	s_cbranch_scc0 .LBB0_657

; #define GAS __attribute__((address_space(1)))
; #define INP(T, k) ((const T*)launder(a.in[k]))
; __device__ __forceinline__ void ph_misc(const Args& a, char* lds, int l) {
;     ...
;             const f32x4 bf = *(const f32x4*)(INP(float, 5) + l * 4); float c0 = 0.f, c1 = 0.f, c2 = 0.f, c3 = 0.f;
; #pragma unroll 4
;             for (int jj = 0; jj < SEQ / 64; ++jj) { const int pos = jj * 64 + lane; const f32x4 y = *(const GAS f32x4*)(FF + (size_t)(b * SEQ + pos) * 4) + bf;
;                 float s0 = fminf(y.x, 0.f) - __logf(1.0f + __expf(-fabsf(y.x))), s1 = fminf(y.y, 0.f) - __logf(1.0f + __expf(-fabsf(y.y)));
;                 float s2 = fminf(y.z, 0.f) - __logf(1.0f + __expf(-fabsf(y.z))), s3 = fminf(y.w, 0.f) - __logf(1.0f + __expf(-fabsf(y.w)));
; #pragma unroll
;                 for (int o = 1; o < 64; o <<= 1) { const float t0 = __shfl_up(s0, o), t1 = __shfl_up(s1, o), t2 = __shfl_up(s2, o), t3 = __shfl_up(s3, o); if (lane >= o) { s0 += t0; s1 += t1; s2 += t2; s3 += t3; } }
.LBB0_607:
	s_mov_b64 s[0:1], s[46:47]
	s_add_u32 s0, s0, s24
	s_addc_u32 s1, s1, s25
	v_mov_b64_e32 v[2:3], s[0:1]
	flat_load_dwordx4 v[2:5], v[2:3]
	v_and_b32_e32 v12, 64, v243
	v_add_u32_e32 v7, -1, v243
	v_cmp_lt_i32_e32 vcc, v7, v12
	v_add_u32_e32 v13, -2, v243
	v_bfrev_b32_e32 v0, 0.5
	v_cndmask_b32_e32 v7, v7, v243, vcc
	v_cmp_lt_i32_e32 vcc, v13, v12
	v_mov_b32_e32 v20, 0
	v_lshl_or_b32 v0, v243, 2, v0
	v_cndmask_b32_e32 v13, v13, v243, vcc
	v_lshlrev_b32_e32 v37, 2, v13
	v_add_u32_e32 v13, -4, v243
	v_cmp_lt_i32_e32 vcc, v13, v12
	v_lshlrev_b32_e32 v7, 2, v7
	s_mov_b32 s28, 32
	v_cndmask_b32_e32 v13, v13, v243, vcc
	v_lshlrev_b32_e32 v39, 2, v13
	v_add_u32_e32 v13, -8, v243
	v_cmp_lt_i32_e32 vcc, v13, v12
	v_mov_b64_e32 v[14:15], v[10:11]
	v_mov_b32_e32 v21, v20
	v_cndmask_b32_e32 v13, v13, v243, vcc
	v_lshlrev_b32_e32 v40, 2, v13
	v_add_u32_e32 v13, -16, v243
	v_cmp_lt_i32_e32 vcc, v13, v12
	v_mov_b32_e32 v22, v20
	v_mov_b32_e32 v23, v20
	v_cndmask_b32_e32 v13, v13, v243, vcc
	v_lshlrev_b32_e32 v41, 2, v13
	v_subrev_u32_e32 v13, 32, v243
	v_cmp_lt_i32_e32 vcc, v13, v12
	s_nop 1
	v_cndmask_b32_e32 v12, v13, v243, vcc
	v_lshlrev_b32_e32 v42, 2, v12
	v_mov_b64_e32 v[12:13], v[8:9]
	v_lshl_add_u64 v[216:217], s[22:23], 0, v[12:13]
	v_add_co_u32_e32 v216, vcc, 0x321c0000, v216
	s_nop 1
	v_addc_co_u32_e32 v217, vcc, 0, v217, vcc
	global_load_dwordx4 v[200:203], v[216:217], off
	global_load_dwordx4 v[204:207], v[216:217], off offset:1024
	global_load_dwordx4 v[208:211], v[216:217], off offset:2048
	global_load_dwordx4 v[212:215], v[216:217], off offset:3072
	s_waitcnt vmcnt(0)
	s_branch .LBB0_609

; #define GAS __attribute__((address_space(1)))
; __device__ __forceinline__ void ph_misc(const Args& a, char* lds, int l) {
;     ...
;             for (int jj = 0; jj < SEQ / 64; ++jj) { const int pos = jj * 64 + lane; const f32x4 y = *(const GAS f32x4*)(FF + (size_t)(b * SEQ + pos) * 4) + bf;
;                 float s0 = fminf(y.x, 0.f) - __logf(1.0f + __expf(-fabsf(y.x))), s1 = fminf(y.y, 0.f) - __logf(1.0f + __expf(-fabsf(y.y)));
;                 float s2 = fminf(y.z, 0.f) - __logf(1.0f + __expf(-fabsf(y.z))), s3 = fminf(y.w, 0.f) - __logf(1.0f + __expf(-fabsf(y.w)));
; #pragma unroll
;                 for (int o = 1; o < 64; o <<= 1) { const float t0 = __shfl_up(s0, o), t1 = __shfl_up(s1, o), t2 = __shfl_up(s2, o), t3 = __shfl_up(s3, o); if (lane >= o) { s0 += t0; s1 += t1; s2 += t2; s3 += t3; } }
.LBB0_609:
	v_lshl_add_u64 v[18:19], s[22:23], 0, v[12:13]
	v_add_co_u32_e32 v16, vcc, 0x321c0000, v18
	s_nop 1
	v_addc_co_u32_e32 v17, vcc, 0, v19, vcc
	s_mov_b64 s[0:1], 0x1000
	v_lshl_add_u64 v[216:217], v[16:17], 0, s[0:1]
	s_waitcnt vmcnt(19) lgkmcnt(0)
	v_mov_b64_e32 v[24:25], v[200:201]
	v_mov_b64_e32 v[26:27], v[202:203]
	global_load_dwordx4 v[200:203], v[216:217], off
	v_pk_add_f32 v[24:25], v[2:3], v[24:25]
	v_pk_add_f32 v[16:17], v[4:5], v[26:27]
	v_min_f32_e32 v27, 0, v24
	v_mul_f32_e64 v24, |v24|, s33
	v_min_f32_e32 v26, 0, v25
	v_mul_f32_e64 v25, |v25|, s33
	v_exp_f32_e32 v24, v24
	v_min_f32_e32 v29, 0, v16
	v_mul_f32_e64 v16, |v16|, s33
	v_exp_f32_e32 v25, v25
	v_min_f32_e32 v28, 0, v17
	v_mul_f32_e64 v17, |v17|, s33
	v_exp_f32_e32 v16, v16
	v_exp_f32_e32 v17, v17
	v_add_f32_e32 v24, 1.0, v24
	v_add_f32_e32 v25, 1.0, v25
	v_cmp_gt_f32_e32 vcc, s90, v24
	v_add_f32_e32 v16, 1.0, v16
	v_cmp_gt_f32_e64 s[16:17], s90, v25
	v_cndmask_b32_e64 v30, 0, 32, vcc
	v_add_f32_e32 v17, 1.0, v17
	v_cndmask_b32_e64 v31, 0, 32, s[16:17]
	v_cmp_gt_f32_e64 s[18:19], s90, v16
	v_ldexp_f32 v24, v24, v30
	v_cmp_gt_f32_e64 s[20:21], s90, v17
	v_cndmask_b32_e64 v32, 0, 32, s[18:19]
	v_ldexp_f32 v25, v25, v31
	v_log_f32_e32 v24, v24
	v_cndmask_b32_e64 v33, 0, 32, s[20:21]
	v_ldexp_f32 v16, v16, v32
	v_log_f32_e32 v25, v25
	v_ldexp_f32 v17, v17, v33
	v_log_f32_e32 v16, v16
	v_log_f32_e32 v17, v17
	v_mul_f32_e32 v34, 0x3f317217, v24
	v_mul_f32_e32 v35, 0x3f317217, v25
	v_fma_f32 v34, v24, s91, -v34
	v_mul_f32_e32 v43, 0x3f317217, v16
	v_fma_f32 v35, v25, s91, -v35
	v_fmac_f32_e32 v34, 0x3377d1cf, v24
	v_cndmask_b32_e32 v30, 0, v246, vcc
	v_mul_f32_e32 v44, 0x3f317217, v17
	v_fma_f32 v43, v16, s91, -v43
	v_fmac_f32_e32 v35, 0x3377d1cf, v25
	v_fmac_f32_e32 v34, 0x3f317217, v24
	v_cmp_lt_f32_e64 vcc, |v24|, s3
	v_fma_f32 v44, v17, s91, -v44
	v_fmac_f32_e32 v43, 0x3377d1cf, v16
	v_fmac_f32_e32 v35, 0x3f317217, v25
	v_cndmask_b32_e32 v24, v24, v34, vcc
	v_cmp_lt_f32_e64 vcc, |v25|, s3
	v_fmac_f32_e32 v44, 0x3377d1cf, v17
	v_fmac_f32_e32 v43, 0x3f317217, v16
	v_cndmask_b32_e32 v25, v25, v35, vcc
	v_cmp_lt_f32_e64 vcc, |v16|, s3
	v_fmac_f32_e32 v44, 0x3f317217, v17
	v_cndmask_b32_e64 v31, 0, v246, s[16:17]
	v_cndmask_b32_e32 v34, v16, v43, vcc
	v_cmp_lt_f32_e64 vcc, |v17|, s3
	v_cndmask_b32_e64 v32, 0, v246, s[18:19]
	v_cndmask_b32_e64 v33, 0, v246, s[20:21]
	v_cndmask_b32_e32 v35, v17, v44, vcc
	v_sub_f32_e32 v17, v24, v30
	v_sub_f32_e32 v16, v25, v31
	v_sub_f32_e32 v31, v34, v32
	v_sub_f32_e32 v30, v35, v33
	v_pk_add_f32 v[24:25], v[26:27], v[16:17] neg_lo:[0,1] neg_hi:[0,1]
	v_pk_add_f32 v[28:29], v[28:29], v[30:31] neg_lo:[0,1] neg_hi:[0,1]
	ds_bpermute_b32 v17, v7, v25
	ds_bpermute_b32 v16, v7, v24
	ds_bpermute_b32 v27, v7, v29
	ds_bpermute_b32 v26, v7, v28
	s_and_saveexec_b64 s[0:1], s[14:15]
	s_cbranch_execz .LBB0_611
	s_waitcnt lgkmcnt(0)
	v_pk_add_f32 v[28:29], v[28:29], v[26:27]
	v_pk_add_f32 v[24:25], v[24:25], v[16:17]

; #define GAS __attribute__((address_space(1)))
; __device__ __forceinline__ void ph_misc(const Args& a, char* lds, int l) {
;     ...
;             for (int jj = 0; jj < SEQ / 64; ++jj) { const int pos = jj * 64 + lane; const f32x4 y = *(const GAS f32x4*)(FF + (size_t)(b * SEQ + pos) * 4) + bf;
;                 float s0 = fminf(y.x, 0.f) - __logf(1.0f + __expf(-fabsf(y.x))), s1 = fminf(y.y, 0.f) - __logf(1.0f + __expf(-fabsf(y.y)));
;                 float s2 = fminf(y.z, 0.f) - __logf(1.0f + __expf(-fabsf(y.z))), s3 = fminf(y.w, 0.f) - __logf(1.0f + __expf(-fabsf(y.w)));
; #pragma unroll
;                 for (int o = 1; o < 64; o <<= 1) { const float t0 = __shfl_up(s0, o), t1 = __shfl_up(s1, o), t2 = __shfl_up(s2, o), t3 = __shfl_up(s3, o); if (lane >= o) { s0 += t0; s1 += t1; s2 += t2; s3 += t3; } }
;                 *(GAS float*)(CUMF + (size_t)(b * 4 + 0) * SEQ + pos) = (c0 + s0) * LOG2E; *(GAS float*)(CUMF + (size_t)(b * 4 + 1) * SEQ + pos) = (c1 + s1) * LOG2E;
;                 *(GAS float*)(CUMF + (size_t)(b * 4 + 2) * SEQ + pos) = (c2 + s2) * LOG2E; *(GAS float*)(CUMF + (size_t)(b * 4 + 3) * SEQ + pos) = (c3 + s3) * LOG2E;
;                 c0 += __shfl(s0, 63); c1 += __shfl(s1, 63); c2 += __shfl(s2, 63); c3 += __shfl(s3, 63); }
.LBB0_621:
	s_or_b64 exec, exec, s[0:1]
	s_waitcnt lgkmcnt(2)
	v_add_f32_e32 v16, v20, v25
	v_mul_f32_e32 v30, 0x3fb8aa3b, v16
	v_lshl_add_u64 v[16:17], s[22:23], 0, v[14:15]
	s_waitcnt lgkmcnt(0)
	v_add_co_u32_e32 v26, vcc, 0x32200000, v16
	s_mov_b32 s0, 0x321c0000
	s_nop 0
	v_addc_co_u32_e32 v27, vcc, 0, v17, vcc
	global_store_dword v[26:27], v30, off
	v_add_f32_e32 v26, v21, v24
	v_mul_f32_e32 v30, 0x3fb8aa3b, v26
	v_add_co_u32_e32 v26, vcc, 0x32202000, v16
	s_nop 1
	v_addc_co_u32_e32 v27, vcc, 0, v17, vcc
	global_store_dword v[26:27], v30, off
	v_add_f32_e32 v26, v22, v29
	v_mul_f32_e32 v30, 0x3fb8aa3b, v26
	v_add_co_u32_e32 v26, vcc, 0x32204000, v16
	s_nop 1
	v_addc_co_u32_e32 v27, vcc, 0, v17, vcc
	global_store_dword v[26:27], v30, off
	v_add_f32_e32 v26, v23, v28
	v_mul_f32_e32 v30, 0x3fb8aa3b, v26
	v_add_co_u32_e32 v26, vcc, 0x32206000, v16
	s_nop 1
	v_addc_co_u32_e32 v27, vcc, 0, v17, vcc
	v_add_co_u32_e32 v18, vcc, s0, v18
	global_store_dword v[26:27], v30, off
	s_nop 0
	v_addc_co_u32_e32 v19, vcc, 0, v19, vcc
	ds_bpermute_b32 v26, v0, v25
	ds_bpermute_b32 v27, v0, v24
	ds_bpermute_b32 v24, v0, v29
	ds_bpermute_b32 v25, v0, v28
	s_waitcnt vmcnt(19)
	v_mov_b64_e32 v[30:31], v[204:205]
	v_mov_b64_e32 v[32:33], v[206:207]
	global_load_dwordx4 v[204:207], v[216:217], off offset:1024
	v_pk_add_f32 v[30:31], v[2:3], v[30:31]
	s_nop 0
	v_mul_f32_e64 v34, |v30|, s33
	v_pk_add_f32 v[28:29], v[4:5], v[32:33]
	v_mul_f32_e64 v35, |v31|, s33
	v_exp_f32_e32 v34, v34
	v_min_f32_e32 v32, 0, v31
	v_min_f32_e32 v31, 0, v28
	v_mul_f32_e64 v28, |v28|, s33
	v_exp_f32_e32 v35, v35
	v_min_f32_e32 v33, 0, v30
	v_min_f32_e32 v30, 0, v29
	v_mul_f32_e64 v29, |v29|, s33
	v_exp_f32_e32 v28, v28
	v_exp_f32_e32 v29, v29
	v_add_f32_e32 v34, 1.0, v34
	v_add_f32_e32 v35, 1.0, v35
	v_cmp_gt_f32_e32 vcc, s90, v34
	v_add_f32_e32 v28, 1.0, v28
	v_cmp_gt_f32_e64 s[16:17], s90, v35
	v_cndmask_b32_e64 v43, 0, 32, vcc
	v_add_f32_e32 v29, 1.0, v29
	v_cndmask_b32_e64 v44, 0, 32, s[16:17]
	v_cmp_gt_f32_e64 s[18:19], s90, v28
	v_ldexp_f32 v34, v34, v43
	v_cmp_gt_f32_e64 s[20:21], s90, v29
	v_cndmask_b32_e64 v45, 0, 32, s[18:19]
	v_ldexp_f32 v35, v35, v44
	v_log_f32_e32 v34, v34
	v_cndmask_b32_e64 v46, 0, 32, s[20:21]
	v_ldexp_f32 v28, v28, v45
	v_log_f32_e32 v35, v35
	v_ldexp_f32 v29, v29, v46
	v_log_f32_e32 v28, v28
	v_log_f32_e32 v46, v29
	v_mul_f32_e32 v29, 0x3f317217, v34
	v_mul_f32_e32 v47, 0x3f317217, v35
	v_fma_f32 v29, v34, s91, -v29
	v_mul_f32_e32 v48, 0x3f317217, v28
	v_fma_f32 v47, v35, s91, -v47
	v_fmac_f32_e32 v29, 0x3377d1cf, v34
	v_cndmask_b32_e32 v43, 0, v246, vcc
	v_mul_f32_e32 v49, 0x3f317217, v46
	v_fma_f32 v48, v28, s91, -v48
	v_fmac_f32_e32 v47, 0x3377d1cf, v35
	v_fmac_f32_e32 v29, 0x3f317217, v34
	v_cmp_lt_f32_e64 vcc, |v34|, s3
	v_fma_f32 v49, v46, s91, -v49
	v_fmac_f32_e32 v48, 0x3377d1cf, v28
	v_fmac_f32_e32 v47, 0x3f317217, v35
	v_cndmask_b32_e32 v29, v34, v29, vcc
	v_cmp_lt_f32_e64 vcc, |v35|, s3
	v_cndmask_b32_e64 v44, 0, v246, s[16:17]
	v_fmac_f32_e32 v49, 0x3377d1cf, v46
	v_fmac_f32_e32 v48, 0x3f317217, v28
	v_cndmask_b32_e32 v34, v35, v47, vcc
	v_cmp_lt_f32_e64 vcc, |v28|, s3
	v_fmac_f32_e32 v49, 0x3f317217, v46
	v_sub_f32_e32 v29, v29, v43
	v_cndmask_b32_e32 v35, v28, v48, vcc
	v_sub_f32_e32 v28, v34, v44
	v_cmp_lt_f32_e64 vcc, |v46|, s3
	v_cndmask_b32_e64 v45, 0, v246, s[18:19]
	v_pk_add_f32 v[28:29], v[32:33], v[28:29] neg_lo:[0,1] neg_hi:[0,1]
	v_cndmask_b32_e32 v32, v46, v49, vcc
	v_cndmask_b32_e64 v33, 0, v246, s[20:21]
	v_sub_f32_e32 v35, v35, v45
	v_sub_f32_e32 v34, v32, v33
	v_pk_add_f32 v[30:31], v[30:31], v[34:35] neg_lo:[0,1] neg_hi:[0,1]
	ds_bpermute_b32 v33, v7, v29
	ds_bpermute_b32 v32, v7, v28
	ds_bpermute_b32 v35, v7, v31
	ds_bpermute_b32 v34, v7, v30
	s_and_saveexec_b64 s[0:1], s[14:15]
	s_cbranch_execz .LBB0_623
	s_waitcnt lgkmcnt(0)
	v_pk_add_f32 v[30:31], v[30:31], v[34:35]
	v_pk_add_f32 v[28:29], v[28:29], v[32:33]

; #define GAS __attribute__((address_space(1)))
; __device__ __forceinline__ void ph_misc(const Args& a, char* lds, int l) {
;     ...
;             for (int jj = 0; jj < SEQ / 64; ++jj) { const int pos = jj * 64 + lane; const f32x4 y = *(const GAS f32x4*)(FF + (size_t)(b * SEQ + pos) * 4) + bf;
;                 float s0 = fminf(y.x, 0.f) - __logf(1.0f + __expf(-fabsf(y.x))), s1 = fminf(y.y, 0.f) - __logf(1.0f + __expf(-fabsf(y.y)));
;                 float s2 = fminf(y.z, 0.f) - __logf(1.0f + __expf(-fabsf(y.z))), s3 = fminf(y.w, 0.f) - __logf(1.0f + __expf(-fabsf(y.w)));
; #pragma unroll
;                 for (int o = 1; o < 64; o <<= 1) { const float t0 = __shfl_up(s0, o), t1 = __shfl_up(s1, o), t2 = __shfl_up(s2, o), t3 = __shfl_up(s3, o); if (lane >= o) { s0 += t0; s1 += t1; s2 += t2; s3 += t3; } }
;                 *(GAS float*)(CUMF + (size_t)(b * 4 + 0) * SEQ + pos) = (c0 + s0) * LOG2E; *(GAS float*)(CUMF + (size_t)(b * 4 + 1) * SEQ + pos) = (c1 + s1) * LOG2E;
;                 *(GAS float*)(CUMF + (size_t)(b * 4 + 2) * SEQ + pos) = (c2 + s2) * LOG2E; *(GAS float*)(CUMF + (size_t)(b * 4 + 3) * SEQ + pos) = (c3 + s3) * LOG2E;
;                 c0 += __shfl(s0, 63); c1 += __shfl(s1, 63); c2 += __shfl(s2, 63); c3 += __shfl(s3, 63); }
.LBB0_633:
	s_or_b64 exec, exec, s[0:1]
	v_pk_add_f32 v[20:21], v[20:21], v[26:27]
	v_pk_add_f32 v[22:23], v[22:23], v[24:25]
	v_add_f32_e32 v24, v20, v29
	s_mov_b32 s0, 0x32200000
	v_mul_f32_e32 v26, 0x3fb8aa3b, v24
	v_add_co_u32_e32 v24, vcc, s0, v16
	s_mov_b32 s0, 0x32202000
	s_nop 0
	v_addc_co_u32_e32 v25, vcc, 0, v17, vcc
	global_store_dword v[24:25], v26, off offset:256
	v_add_f32_e32 v24, v21, v28
	v_mul_f32_e32 v26, 0x3fb8aa3b, v24
	v_add_co_u32_e32 v24, vcc, s0, v16
	s_mov_b32 s0, 0x32204000
	s_nop 0
	v_addc_co_u32_e32 v25, vcc, 0, v17, vcc
	global_store_dword v[24:25], v26, off offset:256
	v_add_f32_e32 v24, v22, v31
	v_mul_f32_e32 v26, 0x3fb8aa3b, v24
	v_add_co_u32_e32 v24, vcc, s0, v16
	s_mov_b32 s0, 0x32206000
	s_nop 0
	v_addc_co_u32_e32 v25, vcc, 0, v17, vcc
	global_store_dword v[24:25], v26, off offset:256
	v_add_f32_e32 v24, v23, v30
	v_mul_f32_e32 v26, 0x3fb8aa3b, v24
	v_add_co_u32_e32 v24, vcc, s0, v16
	ds_bpermute_b32 v27, v0, v28
	s_nop 0
	v_addc_co_u32_e32 v25, vcc, 0, v17, vcc
	global_store_dword v[24:25], v26, off offset:256
	s_waitcnt lgkmcnt(1)
	ds_bpermute_b32 v24, v0, v31
	ds_bpermute_b32 v25, v0, v30
	ds_bpermute_b32 v26, v0, v29
	s_waitcnt vmcnt(19)
	v_mov_b64_e32 v[32:33], v[208:209]
	v_mov_b64_e32 v[34:35], v[210:211]
	global_load_dwordx4 v[208:211], v[216:217], off offset:2048
	v_pk_add_f32 v[30:31], v[2:3], v[32:33]
	v_pk_add_f32 v[28:29], v[4:5], v[34:35]
	v_mul_f32_e64 v34, |v30|, s33
	v_mul_f32_e64 v35, |v31|, s33
	v_exp_f32_e32 v34, v34
	v_min_f32_e32 v32, 0, v31
	v_min_f32_e32 v31, 0, v28
	v_mul_f32_e64 v28, |v28|, s33
	v_exp_f32_e32 v35, v35
	v_min_f32_e32 v33, 0, v30
	v_min_f32_e32 v30, 0, v29
	v_mul_f32_e64 v29, |v29|, s33
	v_exp_f32_e32 v28, v28
	v_exp_f32_e32 v29, v29
	v_add_f32_e32 v34, 1.0, v34
	v_add_f32_e32 v35, 1.0, v35
	v_cmp_gt_f32_e32 vcc, s90, v34
	v_add_f32_e32 v28, 1.0, v28
	v_cmp_gt_f32_e64 s[16:17], s90, v35
	v_cndmask_b32_e64 v43, 0, 32, vcc
	v_add_f32_e32 v29, 1.0, v29
	v_cndmask_b32_e64 v44, 0, 32, s[16:17]
	v_cmp_gt_f32_e64 s[18:19], s90, v28
	v_ldexp_f32 v34, v34, v43
	v_cmp_gt_f32_e64 s[20:21], s90, v29
	v_cndmask_b32_e64 v45, 0, 32, s[18:19]
	v_ldexp_f32 v35, v35, v44
	v_log_f32_e32 v34, v34
	v_cndmask_b32_e64 v46, 0, 32, s[20:21]
	v_ldexp_f32 v28, v28, v45
	v_log_f32_e32 v35, v35
	v_ldexp_f32 v29, v29, v46
	v_log_f32_e32 v28, v28
	v_log_f32_e32 v29, v29
	v_mul_f32_e32 v47, 0x3f317217, v34
	v_mul_f32_e32 v48, 0x3f317217, v35
	v_fma_f32 v47, v34, s91, -v47
	v_mul_f32_e32 v49, 0x3f317217, v28
	v_fma_f32 v48, v35, s91, -v48
	v_fmac_f32_e32 v47, 0x3377d1cf, v34
	v_cndmask_b32_e32 v43, 0, v246, vcc
	v_mul_f32_e32 v50, 0x3f317217, v29
	v_fma_f32 v49, v28, s91, -v49
	v_fmac_f32_e32 v48, 0x3377d1cf, v35
	v_fmac_f32_e32 v47, 0x3f317217, v34
	v_cmp_lt_f32_e64 vcc, |v34|, s3
	v_fma_f32 v50, v29, s91, -v50
	v_fmac_f32_e32 v49, 0x3377d1cf, v28
	v_fmac_f32_e32 v48, 0x3f317217, v35
	v_cndmask_b32_e32 v34, v34, v47, vcc
	v_cmp_lt_f32_e64 vcc, |v35|, s3
	v_fmac_f32_e32 v50, 0x3377d1cf, v29
	v_fmac_f32_e32 v49, 0x3f317217, v28
	v_cndmask_b32_e32 v35, v35, v48, vcc
	v_cmp_lt_f32_e64 vcc, |v28|, s3
	v_fmac_f32_e32 v50, 0x3f317217, v29
	v_cndmask_b32_e64 v44, 0, v246, s[16:17]
	v_cndmask_b32_e32 v47, v28, v49, vcc
	v_cmp_lt_f32_e64 vcc, |v29|, s3
	v_cndmask_b32_e64 v45, 0, v246, s[18:19]
	v_cndmask_b32_e64 v46, 0, v246, s[20:21]
	v_cndmask_b32_e32 v48, v29, v50, vcc
	v_sub_f32_e32 v29, v34, v43
	v_sub_f32_e32 v28, v35, v44
	v_sub_f32_e32 v35, v47, v45
	v_sub_f32_e32 v34, v48, v46
	v_pk_add_f32 v[28:29], v[32:33], v[28:29] neg_lo:[0,1] neg_hi:[0,1]
	v_pk_add_f32 v[30:31], v[30:31], v[34:35] neg_lo:[0,1] neg_hi:[0,1]
	ds_bpermute_b32 v33, v7, v29
	ds_bpermute_b32 v32, v7, v28
	ds_bpermute_b32 v35, v7, v31
	ds_bpermute_b32 v34, v7, v30
	s_and_saveexec_b64 s[0:1], s[14:15]
	s_cbranch_execz .LBB0_635
	s_waitcnt lgkmcnt(0)
	v_pk_add_f32 v[30:31], v[30:31], v[34:35]
	v_pk_add_f32 v[28:29], v[28:29], v[32:33]

; #define GAS __attribute__((address_space(1)))
; __device__ __forceinline__ void ph_misc(const Args& a, char* lds, int l) {
;     ...
;             for (int jj = 0; jj < SEQ / 64; ++jj) { const int pos = jj * 64 + lane; const f32x4 y = *(const GAS f32x4*)(FF + (size_t)(b * SEQ + pos) * 4) + bf;
;                 float s0 = fminf(y.x, 0.f) - __logf(1.0f + __expf(-fabsf(y.x))), s1 = fminf(y.y, 0.f) - __logf(1.0f + __expf(-fabsf(y.y)));
;                 float s2 = fminf(y.z, 0.f) - __logf(1.0f + __expf(-fabsf(y.z))), s3 = fminf(y.w, 0.f) - __logf(1.0f + __expf(-fabsf(y.w)));
; #pragma unroll
;                 for (int o = 1; o < 64; o <<= 1) { const float t0 = __shfl_up(s0, o), t1 = __shfl_up(s1, o), t2 = __shfl_up(s2, o), t3 = __shfl_up(s3, o); if (lane >= o) { s0 += t0; s1 += t1; s2 += t2; s3 += t3; } }
;                 *(GAS float*)(CUMF + (size_t)(b * 4 + 0) * SEQ + pos) = (c0 + s0) * LOG2E; *(GAS float*)(CUMF + (size_t)(b * 4 + 1) * SEQ + pos) = (c1 + s1) * LOG2E;
;                 *(GAS float*)(CUMF + (size_t)(b * 4 + 2) * SEQ + pos) = (c2 + s2) * LOG2E; *(GAS float*)(CUMF + (size_t)(b * 4 + 3) * SEQ + pos) = (c3 + s3) * LOG2E;
;                 c0 += __shfl(s0, 63); c1 += __shfl(s1, 63); c2 += __shfl(s2, 63); c3 += __shfl(s3, 63); }
.LBB0_645:
	s_or_b64 exec, exec, s[0:1]
	v_pk_add_f32 v[20:21], v[20:21], v[26:27]
	v_pk_add_f32 v[22:23], v[22:23], v[24:25]
	v_add_f32_e32 v24, v20, v29
	v_mul_f32_e32 v26, 0x3fb8aa3b, v24
	v_add_co_u32_e32 v24, vcc, 0x32200000, v16
	s_nop 1
	v_addc_co_u32_e32 v25, vcc, 0, v17, vcc
	global_store_dword v[24:25], v26, off offset:512
	v_add_f32_e32 v24, v21, v28
	v_mul_f32_e32 v26, 0x3fb8aa3b, v24
	v_add_co_u32_e32 v24, vcc, 0x32202000, v16
	s_nop 1
	v_addc_co_u32_e32 v25, vcc, 0, v17, vcc
	global_store_dword v[24:25], v26, off offset:512
	v_add_f32_e32 v24, v22, v31
	v_mul_f32_e32 v26, 0x3fb8aa3b, v24
	v_add_co_u32_e32 v24, vcc, 0x32204000, v16
	s_nop 1
	v_addc_co_u32_e32 v25, vcc, 0, v17, vcc
	global_store_dword v[24:25], v26, off offset:512
	v_add_f32_e32 v24, v23, v30
	v_mul_f32_e32 v26, 0x3fb8aa3b, v24
	v_add_co_u32_e32 v24, vcc, 0x32206000, v16
	s_nop 1
	v_addc_co_u32_e32 v25, vcc, 0, v17, vcc
	global_store_dword v[24:25], v26, off offset:512
	s_waitcnt lgkmcnt(0)
	ds_bpermute_b32 v24, v0, v29
	ds_bpermute_b32 v25, v0, v28
	ds_bpermute_b32 v18, v0, v31
	ds_bpermute_b32 v19, v0, v30
	s_waitcnt vmcnt(19)
	v_mov_b64_e32 v[32:33], v[212:213]
	v_mov_b64_e32 v[34:35], v[214:215]
	global_load_dwordx4 v[212:215], v[216:217], off offset:3072
	v_pk_add_f32 v[28:29], v[2:3], v[32:33]
	s_nop 0
	v_min_f32_e32 v31, 0, v28
	v_mul_f32_e64 v28, |v28|, s33
	v_pk_add_f32 v[26:27], v[4:5], v[34:35]
	v_min_f32_e32 v30, 0, v29
	v_mul_f32_e64 v29, |v29|, s33
	v_exp_f32_e32 v28, v28
	v_min_f32_e32 v33, 0, v26
	v_mul_f32_e64 v26, |v26|, s33
	v_exp_f32_e32 v29, v29
	v_min_f32_e32 v32, 0, v27
	v_mul_f32_e64 v27, |v27|, s33
	v_exp_f32_e32 v26, v26
	v_exp_f32_e32 v27, v27
	v_add_f32_e32 v28, 1.0, v28
	v_add_f32_e32 v29, 1.0, v29
	v_cmp_gt_f32_e32 vcc, s90, v28
	v_add_f32_e32 v26, 1.0, v26
	v_cmp_gt_f32_e64 s[16:17], s90, v29
	v_cndmask_b32_e64 v34, 0, 32, vcc
	v_add_f32_e32 v27, 1.0, v27
	v_cndmask_b32_e64 v35, 0, 32, s[16:17]
	v_cmp_gt_f32_e64 s[18:19], s90, v26
	v_ldexp_f32 v28, v28, v34
	v_cmp_gt_f32_e64 s[20:21], s90, v27
	v_cndmask_b32_e64 v43, 0, 32, s[18:19]
	v_ldexp_f32 v29, v29, v35
	v_log_f32_e32 v28, v28
	v_cndmask_b32_e64 v44, 0, 32, s[20:21]
	v_ldexp_f32 v26, v26, v43
	v_log_f32_e32 v29, v29
	v_ldexp_f32 v27, v27, v44
	v_log_f32_e32 v26, v26
	v_log_f32_e32 v27, v27
	v_mul_f32_e32 v45, 0x3f317217, v28
	v_mul_f32_e32 v46, 0x3f317217, v29
	v_fma_f32 v45, v28, s91, -v45
	v_mul_f32_e32 v47, 0x3f317217, v26
	v_fma_f32 v46, v29, s91, -v46
	v_fmac_f32_e32 v45, 0x3377d1cf, v28
	v_cndmask_b32_e32 v34, 0, v246, vcc
	v_mul_f32_e32 v48, 0x3f317217, v27
	v_fma_f32 v47, v26, s91, -v47
	v_fmac_f32_e32 v46, 0x3377d1cf, v29
	v_fmac_f32_e32 v45, 0x3f317217, v28
	v_cmp_lt_f32_e64 vcc, |v28|, s3
	v_fma_f32 v48, v27, s91, -v48
	v_fmac_f32_e32 v47, 0x3377d1cf, v26
	v_fmac_f32_e32 v46, 0x3f317217, v29
	v_cndmask_b32_e32 v28, v28, v45, vcc
	v_cmp_lt_f32_e64 vcc, |v29|, s3
	v_fmac_f32_e32 v48, 0x3377d1cf, v27
	v_fmac_f32_e32 v47, 0x3f317217, v26
	v_cndmask_b32_e32 v29, v29, v46, vcc
	v_cmp_lt_f32_e64 vcc, |v26|, s3
	v_fmac_f32_e32 v48, 0x3f317217, v27
	v_cndmask_b32_e64 v35, 0, v246, s[16:17]
	v_cndmask_b32_e32 v45, v26, v47, vcc
	v_cmp_lt_f32_e64 vcc, |v27|, s3
	v_cndmask_b32_e64 v43, 0, v246, s[18:19]
	v_cndmask_b32_e64 v44, 0, v246, s[20:21]
	v_cndmask_b32_e32 v46, v27, v48, vcc
	v_sub_f32_e32 v27, v28, v34
	v_sub_f32_e32 v26, v29, v35
	v_sub_f32_e32 v35, v45, v43
	v_sub_f32_e32 v34, v46, v44
	v_pk_add_f32 v[28:29], v[30:31], v[26:27] neg_lo:[0,1] neg_hi:[0,1]
	v_pk_add_f32 v[26:27], v[32:33], v[34:35] neg_lo:[0,1] neg_hi:[0,1]
	ds_bpermute_b32 v31, v7, v29
	ds_bpermute_b32 v30, v7, v28
	ds_bpermute_b32 v33, v7, v27
	ds_bpermute_b32 v32, v7, v26
	s_and_saveexec_b64 s[0:1], s[14:15]
	s_cbranch_execz .LBB0_647
	s_waitcnt lgkmcnt(0)
	v_pk_add_f32 v[26:27], v[26:27], v[32:33]
	v_pk_add_f32 v[28:29], v[28:29], v[30:31]

; #define LAS __attribute__((address_space(3)))
; #define GAS __attribute__((address_space(1)))
; __device__ __forceinline__ unsigned cvtpk(float lo, float hi) { unsigned r; asm volatile("v_cvt_pk_bf16_f32 %0, %1, %2" : "=v"(r) : "v"(lo), "v"(hi)); return r; }
; __device__ __forceinline__ void ph_misc(const Args& a, char* lds, int l) {
;     ...
;     for (int u = blockIdx.x; u < 512; u += G) {
;         const int g = u & 3, bn = u >> 2; const size_t row0 = (size_t)bn * 128;
;         LAS char* Vt = (LAS char*)lds;
;         const bool mine = (lane >> 4) == g; const int cl = (lane & 15) * 8;
;         float gg[8], bb[8];
; #pragma unroll
;         for (int k = 0; k < 8; ++k) { gg[k] = sgu_g[l * 512 + g * 128 + cl + k]; bb[k] = sgu_b[l * 512 + g * 128 + cl + k]; }
;         for (int i = 0; i < 16; i += 2) { const int s0 = wave * 16 + i, s1 = s0 + 1;
;             const bf16x8 va = *(const GAS bf16x8*)(P + (row0 + s0) * NIN + PC_V + lane * 8), vb = *(const GAS bf16x8*)(P + (row0 + s1) * NIN + PC_V + lane * 8);
;     ...
;                 const float vn = __shfl_xor(val, 1); if ((r32 & 1) == 0) *(unsigned*)(MIX + row * DM + 1024 + g * 128 + c) = cvtpk(val, vn); }
;         __syncthreads();
;     }
.LBB0_659:
	s_or_b64 exec, exec, s[0:1]
	s_lshl_b64 s[0:1], s[34:35], 7
	v_lshrrev_b32_e32 v209, 1, v243
	v_and_b32_e32 v210, 1, v243
	v_lshlrev_b32_e32 v211, 7, v209
	v_lshl_add_u32 v211, v210, 6, v211
	v_and_b32_e32 v212, 0xffffffc0, v240
	v_lshlrev_b32_e32 v212, 6, v212
	v_add_u32_e32 v211, v211, v212
	v_add_u32_e32 v211, 0xa000, v211
	s_waitcnt lgkmcnt(0)
	ds_read_b128 v[216:219], v211
	ds_read_b128 v[220:223], v211 offset:16
	ds_read_b128 v[224:227], v211 offset:32
	ds_read_b128 v[228:231], v211 offset:48
	v_lshrrev_b32_e32 v213, 5, v243
	v_lshlrev_b32_e32 v213, 2, v213
	v_sub_u32_e32 v213, v36, v213
	v_add_u32_e32 v213, v213, v209
	v_or_b32_e32 v232, s0, v213
	v_mov_b32_e32 v233, s1
	v_lshlrev_b64 v[232:233], 12, v[232:233]
	v_lshl_add_u64 v[232:233], s[22:23], 0, v[232:233]
	v_lshl_add_u64 v[232:233], v[232:233], 0, s[86:87]
	v_and_b32_e32 v234, 31, v243
	v_sub_u32_e32 v234, v38, v234
	v_lshlrev_b32_e32 v234, 1, v234
	v_lshl_add_u32 v234, v210, 6, v234
	v_mov_b32_e32 v235, 0
	v_lshl_add_u64 v[232:233], v[232:233], 0, v[234:235]
	v_add_co_u32_e32 v232, vcc, 0x271c0000, v232
	s_nop 1
	v_addc_co_u32_e32 v233, vcc, 0, v233, vcc
	s_waitcnt lgkmcnt(0)
	global_store_dwordx4 v[232:233], v[216:219], off offset:2048
	global_store_dwordx4 v[232:233], v[220:223], off offset:2064
	global_store_dwordx4 v[232:233], v[224:227], off offset:2080
	global_store_dwordx4 v[232:233], v[228:231], off offset:2096
	s_add_i32 s37, s37, s78
	s_cmpk_lt_i32 s37, 0x200
	s_waitcnt lgkmcnt(0)
	s_barrier
	s_cbranch_scc0 .LBB0_740
.LBB0_660:
	s_and_b32 s0, s37, 3
	s_lshl_b32 s2, s0, 7
	s_or_b32 s38, s2, s36
	v_or_b32_e32 v0, s38, v41
	v_lshlrev_b64 v[6:7], 2, v[0:1]
	v_lshl_add_u64 v[10:11], s[12:13], 0, v[6:7]
	v_lshl_add_u64 v[14:15], s[10:11], 0, v[6:7]
	flat_load_dwordx4 v[2:5], v[10:11]
	flat_load_dwordx4 v[6:9], v[14:15]
	s_nop 0
	flat_load_dwordx4 v[10:13], v[10:11] offset:16
	s_nop 0
	flat_load_dwordx4 v[14:17], v[14:15] offset:16
	s_ashr_i32 s34, s37, 2
	v_mov_b32_e32 v0, 0x130000
	s_mov_b32 s39, -2
	s_ashr_i32 s35, s34, 31
	v_cmp_eq_u32_e64 s[6:7], s0, v37
	v_mad_i64_i32 v[26:27], s[0:1], s34, v0, v[70:71]
	v_mov_b32_e32 v0, v57
	s_waitcnt vmcnt(0) lgkmcnt(0)
	v_mov_b32_e32 v30, v6
	v_mov_b32_e32 v28, v2
	v_mov_b32_e32 v29, v2
	v_mov_b32_e32 v31, v6
	v_mov_b32_e32 v2, v3
	v_mov_b32_e32 v6, v7
	v_mov_b32_e32 v32, v4
	v_mov_b32_e32 v33, v4
	v_mov_b32_e32 v72, v8
	v_mov_b32_e32 v73, v8
	v_mov_b32_e32 v4, v5
	v_mov_b32_e32 v8, v9
	v_mov_b32_e32 v74, v10
	v_mov_b32_e32 v75, v10
	v_mov_b32_e32 v76, v14
	v_mov_b32_e32 v77, v14
	v_mov_b32_e32 v10, v11
	v_mov_b32_e32 v14, v15
	v_mov_b32_e32 v78, v12
	v_mov_b32_e32 v79, v12
	v_mov_b32_e32 v80, v16
	v_mov_b32_e32 v81, v16
	v_mov_b32_e32 v12, v13
	v_mov_b32_e32 v16, v17
	global_load_dwordx4 v[200:203], v[26:27], off
	v_add_co_u32_e32 v210, vcc, 0x2000, v26
	s_nop 1
	v_addc_co_u32_e32 v211, vcc, 0, v27, vcc
	global_load_dwordx4 v[204:207], v[210:211], off offset:1536
	s_branch .LBB0_662

; #define GAS __attribute__((address_space(1)))
; __device__ __forceinline__ float bf2f(unsigned short h) { return __uint_as_float(((unsigned)h) << 16); }
; __device__ __forceinline__ void ph_misc(const Args& a, char* lds, int l) {
;     ...
;         for (int i = 0; i < 16; i += 2) { const int s0 = wave * 16 + i, s1 = s0 + 1;
;             const bf16x8 va = *(const GAS bf16x8*)(P + (row0 + s0) * NIN + PC_V + lane * 8), vb = *(const GAS bf16x8*)(P + (row0 + s1) * NIN + PC_V + lane * 8);
;             float za[8], zb[8]; float suma = 0.f, sqa = 0.f, sumb = 0.f, sqb = 0.f;
; #pragma unroll
;             for (int k = 0; k < 8; ++k) { za[k] = gelu_tanh(bf2f((unsigned short)va[k])); zb[k] = gelu_tanh(bf2f((unsigned short)vb[k])); suma += za[k]; sqa += za[k] * za[k]; sumb += zb[k]; sqb += zb[k] * zb[k]; }
; #pragma unroll
;             for (int o = 1; o < 64; o <<= 1) { const float t0 = __shfl_xor(suma, o), t1 = __shfl_xor(sqa, o), t2 = __shfl_xor(sumb, o), t3 = __shfl_xor(sqb, o); suma += t0; sqa += t1; sumb += t2; sqb += t3; }
.LBB0_662:
	s_mov_b64 s[0:1], 0x4c00
	v_lshl_add_u64 v[208:209], v[26:27], 0, s[0:1]
	v_add_co_u32_e32 v210, vcc, 0x2000, v208
	s_nop 1
	v_addc_co_u32_e32 v211, vcc, 0, v209, vcc
	s_waitcnt vmcnt(0)
	v_mov_b64_e32 v[18:19], v[200:201]
	v_mov_b64_e32 v[20:21], v[202:203]
	v_mov_b64_e32 v[22:23], v[204:205]
	v_mov_b64_e32 v[24:25], v[206:207]
	global_load_dwordx4 v[200:203], v[208:209], off
	global_load_dwordx4 v[204:207], v[210:211], off offset:1536
	v_lshlrev_b32_e32 v90, 16, v18
	v_and_b32_e32 v92, 0xffff0000, v18
	v_lshlrev_b32_e32 v18, 16, v19
	s_waitcnt lgkmcnt(1)
	v_and_b32_e32 v86, 0xffff0000, v19
	v_lshlrev_b32_e32 v88, 16, v20
	v_mul_f32_e32 v19, 0x3d372713, v90
	v_mul_f32_e32 v63, 0x3d372713, v92
	v_mov_b32_e32 v61, v90
	v_mov_b32_e32 v65, v92
	v_mul_f32_e32 v67, 0x3d372713, v18
	v_mul_f32_e32 v82, 0x3d372713, v86
	v_mul_f32_e32 v84, 0x3d372713, v88
	v_lshlrev_b32_e32 v91, 16, v22
	v_mul_f32_e32 v94, v19, v90
	v_and_b32_e32 v93, 0xffff0000, v22
	v_mul_f32_e32 v22, v63, v92
	v_mov_b32_e32 v69, v18
	v_mov_b32_e32 v83, v86
	v_mov_b32_e32 v85, v88
	v_lshlrev_b32_e32 v19, 16, v23
	v_mul_f32_e32 v63, v67, v18
	s_waitcnt lgkmcnt(0)
	v_and_b32_e32 v87, 0xffff0000, v23
	v_mul_f32_e32 v23, v82, v86
	v_mul_f32_e32 v67, v84, v88
	v_fmac_f32_e32 v61, v94, v61
	v_mul_f32_e32 v82, 0x3d372713, v91
	v_fmac_f32_e32 v65, v22, v65
	v_mul_f32_e32 v22, 0x3d372713, v93
	v_mov_b32_e32 v84, v91
	v_mov_b32_e32 v94, v93
	v_fmac_f32_e32 v69, v63, v69
	v_mul_f32_e32 v63, 0x3d372713, v19
	v_fmac_f32_e32 v83, v23, v83
	v_mul_f32_e32 v23, 0x3d372713, v87
	v_fmac_f32_e32 v85, v67, v85
	v_mul_f32_e32 v61, 0x3f4c422a, v61
	v_mul_f32_e32 v67, v82, v91
	v_mul_f32_e32 v65, 0x3f4c422a, v65
	v_mul_f32_e32 v22, v22, v93
	v_mov_b32_e32 v95, v19
	v_mov_b32_e32 v96, v87
	v_mul_f32_e32 v63, v63, v19
	v_mul_f32_e32 v23, v23, v87
	v_mul_f32_e32 v61, 0xc038aa3b, v61
	v_fmac_f32_e32 v84, v67, v84
	v_mul_f32_e32 v65, 0xc038aa3b, v65
	v_fmac_f32_e32 v94, v22, v94
	v_mul_f32_e32 v69, 0x3f4c422a, v69
	v_mul_f32_e32 v82, 0x3f4c422a, v83
	v_fmac_f32_e32 v95, v63, v95
	v_fmac_f32_e32 v96, v23, v96
	v_exp_f32_e32 v23, v61
	v_mul_f32_e32 v61, 0x3f4c422a, v84
	v_exp_f32_e32 v65, v65
	v_mul_f32_e32 v67, 0x3f4c422a, v94
	v_mul_f32_e32 v22, 0xc038aa3b, v69
	v_mul_f32_e32 v63, 0xc038aa3b, v82
	v_mul_f32_e32 v69, 0x3f4c422a, v95
	v_mul_f32_e32 v61, 0xc038aa3b, v61
	v_mul_f32_e32 v67, 0xc038aa3b, v67
	v_exp_f32_e32 v22, v22
	v_exp_f32_e32 v63, v63
	v_mul_f32_e32 v69, 0xc038aa3b, v69
	v_exp_f32_e32 v61, v61
	v_exp_f32_e32 v67, v67
	v_exp_f32_e32 v69, v69
	v_lshlrev_b32_e32 v89, 16, v24
	v_add_f32_e32 v65, 1.0, v65
	v_add_f32_e32 v23, 1.0, v23
	v_rcp_f32_e32 v94, v65
	v_mul_f32_e32 v65, 0x3d372713, v89
	v_mul_f32_e32 v82, 0x3f4c422a, v96
	v_add_f32_e32 v83, 1.0, v22
	v_add_f32_e32 v63, 1.0, v63
	v_rcp_f32_e32 v22, v23
	v_add_f32_e32 v23, 1.0, v61
	v_add_f32_e32 v61, 1.0, v67
	v_mul_f32_e32 v65, v65, v89
	v_mov_b32_e32 v67, v89
	v_mul_f32_e32 v99, 0x3f4c422a, v85
	v_mul_f32_e32 v82, 0xc038aa3b, v82
	v_rcp_f32_e32 v98, v63
	v_add_f32_e32 v63, 1.0, v69
	v_fmac_f32_e32 v67, v65, v67
	v_exp_f32_e32 v82, v82
	v_rcp_f32_e32 v95, v61
	v_rcp_f32_e32 v97, v63
	v_mul_f32_e32 v63, 0xc038aa3b, v99
	v_mul_f32_e32 v65, 0x3f4c422a, v67
	v_rcp_f32_e32 v23, v23
	v_exp_f32_e32 v63, v63
	v_mul_f32_e32 v65, 0xc038aa3b, v65
	v_exp_f32_e32 v65, v65
	v_and_b32_e32 v104, 0xffff0000, v20
	v_mul_f32_e32 v20, 0x3d372713, v104
	v_rcp_f32_e32 v96, v83
	v_add_f32_e32 v61, 1.0, v82
	v_pk_mul_f32 v[82:83], v[94:95], v[92:93]
	v_and_b32_e32 v105, 0xffff0000, v24
	v_mul_f32_e32 v20, v20, v104
	v_mov_b32_e32 v24, v104
	v_pk_mul_f32 v[84:85], v[22:23], v[90:91]
	v_pk_fma_f32 v[90:91], v[22:23], v[90:91], 0 op_sel_hi:[1,1,0]
	v_pk_mul_f32 v[100:101], v[82:83], v[82:83]
	v_rcp_f32_e32 v99, v61
	v_add_f32_e32 v61, 1.0, v63
	v_fmac_f32_e32 v24, v20, v24
	v_pk_fma_f32 v[102:103], v[94:95], v[92:93], v[90:91]
	v_pk_fma_f32 v[90:91], v[84:85], v[84:85], v[100:101]
	v_rcp_f32_e32 v100, v61
	v_add_f32_e32 v61, 1.0, v65
	v_mul_f32_e32 v20, 0x3f4c422a, v24
	v_mul_f32_e32 v24, 0x3d372713, v105
	v_rcp_f32_e32 v101, v61
	v_mul_f32_e32 v24, v24, v105
	v_mov_b32_e32 v61, v105
	v_fmac_f32_e32 v61, v24, v61
	v_mul_f32_e32 v20, 0xc038aa3b, v20
	v_mul_f32_e32 v24, 0x3f4c422a, v61
	v_exp_f32_e32 v20, v20
	v_mul_f32_e32 v24, 0xc038aa3b, v24
	v_exp_f32_e32 v24, v24
	v_lshlrev_b32_e32 v110, 16, v21
	v_add_f32_e32 v20, 1.0, v20
	v_rcp_f32_e32 v108, v20
	v_add_f32_e32 v20, 1.0, v24
	v_rcp_f32_e32 v109, v20
	v_mul_f32_e32 v20, 0x3d372713, v110
	v_mul_f32_e32 v20, v20, v110
	v_mov_b32_e32 v24, v110
	v_lshlrev_b32_e32 v111, 16, v25
	v_fmac_f32_e32 v24, v20, v24
	v_mul_f32_e32 v20, 0x3f4c422a, v24
	v_mul_f32_e32 v24, 0x3d372713, v111
	v_mul_f32_e32 v24, v24, v111
	v_mov_b32_e32 v61, v111
	v_fmac_f32_e32 v61, v24, v61
	v_mul_f32_e32 v20, 0xc038aa3b, v20
	v_mul_f32_e32 v24, 0x3f4c422a, v61
	v_exp_f32_e32 v20, v20
	v_mul_f32_e32 v24, 0xc038aa3b, v24
	v_exp_f32_e32 v24, v24
	v_and_b32_e32 v114, 0xffff0000, v21
	v_add_f32_e32 v20, 1.0, v20
	v_mul_f32_e32 v21, 0x3d372713, v114
	v_rcp_f32_e32 v112, v20
	v_add_f32_e32 v20, 1.0, v24
	v_mul_f32_e32 v21, v21, v114
	v_mov_b32_e32 v24, v114
	v_and_b32_e32 v115, 0xffff0000, v25
	v_fmac_f32_e32 v24, v21, v24
	v_mul_f32_e32 v21, 0x3f4c422a, v24
	v_mul_f32_e32 v24, 0x3d372713, v115
	v_mul_f32_e32 v24, v24, v115
	v_mov_b32_e32 v25, v115
	v_fmac_f32_e32 v25, v24, v25
	v_mul_f32_e32 v21, 0xc038aa3b, v21
	v_mul_f32_e32 v24, 0x3f4c422a, v25
	v_exp_f32_e32 v21, v21
	v_mul_f32_e32 v24, 0xc038aa3b, v24
	v_exp_f32_e32 v24, v24
	v_rcp_f32_e32 v113, v20
	v_add_f32_e32 v20, 1.0, v21
	v_pk_mul_f32 v[22:23], v[96:97], v[18:19]
	v_rcp_f32_e32 v116, v20
	v_add_f32_e32 v20, 1.0, v24
	v_pk_fma_f32 v[90:91], v[22:23], v[22:23], v[90:91]
	v_pk_mul_f32 v[92:93], v[98:99], v[86:87]
	v_rcp_f32_e32 v117, v20
	v_pk_fma_f32 v[18:19], v[96:97], v[18:19], v[102:103]
	v_pk_fma_f32 v[94:95], v[92:93], v[92:93], v[90:91]
	v_pk_mul_f32 v[90:91], v[100:101], v[88:89]
	v_pk_fma_f32 v[18:19], v[98:99], v[86:87], v[18:19]
	v_pk_fma_f32 v[106:107], v[90:91], v[90:91], v[94:95]
	v_pk_mul_f32 v[94:95], v[108:109], v[104:105]
	v_pk_fma_f32 v[18:19], v[100:101], v[88:89], v[18:19]
	v_pk_fma_f32 v[20:21], v[94:95], v[94:95], v[106:107]
	v_pk_mul_f32 v[24:25], v[112:113], v[110:111]
	v_pk_fma_f32 v[18:19], v[108:109], v[104:105], v[18:19]
	v_pk_fma_f32 v[106:107], v[24:25], v[24:25], v[20:21]
	v_pk_mul_f32 v[20:21], v[116:117], v[114:115]
	v_pk_fma_f32 v[18:19], v[112:113], v[110:111], v[18:19]
	v_pk_fma_f32 v[106:107], v[20:21], v[20:21], v[106:107]
	v_pk_fma_f32 v[18:19], v[116:117], v[114:115], v[18:19]
	ds_bpermute_b32 v61, v43, v106
	ds_bpermute_b32 v63, v43, v107
	ds_bpermute_b32 v86, v43, v18
	ds_bpermute_b32 v87, v43, v19
	s_waitcnt lgkmcnt(3)
; __device__ __forceinline__ void ph_misc(const Args& a, char* lds, int l) {
;     ...
;             for (int o = 1; o < 64; o <<= 1) { const float t0 = __shfl_xor(suma, o), t1 = __shfl_xor(sqa, o), t2 = __shfl_xor(sumb, o), t3 = __shfl_xor(sqb, o); suma += t0; sqa += t1; sumb += t2; sqb += t3; }
	v_add_f32_e32 v61, v106, v61
	s_waitcnt lgkmcnt(2)
	v_add_f32_e32 v63, v107, v63
	ds_bpermute_b32 v65, v45, v61
	s_waitcnt lgkmcnt(1)
	v_pk_add_f32 v[18:19], v[18:19], v[86:87]
	ds_bpermute_b32 v67, v45, v63
	ds_bpermute_b32 v86, v45, v18
	ds_bpermute_b32 v87, v45, v19
	s_waitcnt lgkmcnt(3)
	v_add_f32_e32 v61, v61, v65
	ds_bpermute_b32 v65, v47, v61
	s_waitcnt lgkmcnt(3)
	v_add_f32_e32 v63, v63, v67
	ds_bpermute_b32 v67, v47, v63
	s_waitcnt lgkmcnt(2)
	v_pk_add_f32 v[18:19], v[18:19], v[86:87]
	ds_bpermute_b32 v86, v47, v18
	ds_bpermute_b32 v87, v47, v19
	s_waitcnt lgkmcnt(3)
	v_add_f32_e32 v61, v61, v65
	s_waitcnt lgkmcnt(2)
	v_add_f32_e32 v63, v63, v67
	ds_bpermute_b32 v65, v49, v61
	ds_bpermute_b32 v67, v49, v63
	s_waitcnt lgkmcnt(2)
	v_pk_add_f32 v[18:19], v[18:19], v[86:87]
	ds_bpermute_b32 v86, v49, v18
	ds_bpermute_b32 v87, v49, v19
	s_waitcnt lgkmcnt(3)
	v_add_f32_e32 v61, v61, v65
	s_waitcnt lgkmcnt(2)
	v_add_f32_e32 v63, v63, v67
	ds_bpermute_b32 v65, v51, v61
	ds_bpermute_b32 v67, v51, v63
	s_waitcnt lgkmcnt(2)
	v_pk_add_f32 v[18:19], v[18:19], v[86:87]
	ds_bpermute_b32 v86, v51, v18
	ds_bpermute_b32 v87, v51, v19
	s_waitcnt lgkmcnt(3)
	v_add_f32_e32 v61, v61, v65
	s_waitcnt lgkmcnt(2)
	v_add_f32_e32 v65, v63, v67
	ds_bpermute_b32 v63, v53, v61
	ds_bpermute_b32 v67, v53, v65
	s_waitcnt lgkmcnt(2)
	v_pk_add_f32 v[18:19], v[18:19], v[86:87]
	ds_bpermute_b32 v86, v53, v18
	ds_bpermute_b32 v87, v53, v19
	s_and_saveexec_b64 s[0:1], s[6:7]
	s_cbranch_execz .LBB0_661
; #define LAS __attribute__((address_space(3)))
; __device__ __forceinline__ unsigned f2bf(float f) { unsigned u = __float_as_uint(f); return (u + 0x7fffu + ((u >> 16) & 1u)) >> 16; }
; __device__ __forceinline__ void ph_misc(const Args& a, char* lds, int l) {
;     ...
;             const float meana = suma * (1.0f / 512.0f), meanb = sumb * (1.0f / 512.0f);
;             const float rstda = 1.0f / sqrtf(fmaxf(sqa * (1.0f / 512.0f) - meana * meana, 0.f) + EPSN), rstdb = 1.0f / sqrtf(fmaxf(sqb * (1.0f / 512.0f) - meanb * meanb, 0.f) + EPSN);
;             if (mine) {
; #pragma unroll
;                 for (int k = 0; k < 8; ++k) { *(LAS bf16_t*)(Vt + (cl + k) * 272 + s0 * 2) = (bf16_t)f2bf((za[k] - meana) * rstda * gg[k] + bb[k]);
;                                               *(LAS bf16_t*)(Vt + (cl + k) * 272 + s1 * 2) = (bf16_t)f2bf((zb[k] - meanb) * rstdb * gg[k] + bb[k]); } } }
	s_waitcnt lgkmcnt(0)
	v_pk_add_f32 v[18:19], v[18:19], v[86:87]
	v_add_f32_e32 v88, v65, v67
	v_pk_mul_f32 v[86:87], v[18:19], s[42:43] op_sel_hi:[1,0]
	s_mov_b32 s40, 0xf800000
	v_mov_b32_e32 v89, v87
	v_mov_b32_e32 v195, v87
	v_pk_mul_f32 v[88:89], v[88:89], v[194:195]
	v_mov_b32_e32 v195, v86
	v_sub_f32_e32 v65, v88, v89
	v_max_f32_e32 v65, 0, v65
	v_add_f32_e32 v65, 0x358637bd, v65
	v_mul_f32_e32 v67, 0x4f800000, v65
	v_cmp_gt_f32_e32 vcc, s40, v65
	v_add_f32_e32 v88, v61, v63
	v_mov_b32_e32 v89, v86
	v_cndmask_b32_e32 v65, v65, v67, vcc
	v_sqrt_f32_e32 v67, v65
	v_pk_mul_f32 v[86:87], v[88:89], v[194:195]
	v_pk_fma_f32 v[84:85], v[18:19], s[42:43], v[84:85] op_sel_hi:[1,0,1] neg_lo:[1,0,0] neg_hi:[1,0,0]
	v_pk_fma_f32 v[82:83], v[18:19], s[42:43], v[82:83] op_sel_hi:[1,0,1] neg_lo:[1,0,0] neg_hi:[1,0,0]
	v_add_u32_e32 v61, -1, v67
	v_fma_f32 v63, -v61, v67, v65
	v_cmp_ge_f32_e64 s[8:9], 0, v63
	v_add_u32_e32 v63, 1, v67
	v_pk_fma_f32 v[22:23], v[18:19], s[42:43], v[22:23] op_sel_hi:[1,0,1] neg_lo:[1,0,0] neg_hi:[1,0,0]
	v_cndmask_b32_e64 v61, v67, v61, s[8:9]
	v_fma_f32 v67, -v63, v67, v65
	v_cmp_lt_f32_e64 s[8:9], 0, v67
	v_sub_f32_e32 v67, v86, v87
	v_max_f32_e32 v67, 0, v67
	v_add_f32_e32 v67, 0x358637bd, v67
	v_cndmask_b32_e64 v61, v61, v63, s[8:9]
	v_mul_f32_e32 v69, 0x4f800000, v67
	v_cmp_gt_f32_e64 s[8:9], s40, v67
	v_mul_f32_e32 v63, 0x37800000, v61
	v_cndmask_b32_e32 v61, v61, v63, vcc
	v_cndmask_b32_e64 v67, v67, v69, s[8:9]
	v_sqrt_f32_e32 v69, v67
	v_cmp_class_f32_e32 vcc, v65, v247
	v_add_u32_e32 v63, -1, v69
	s_nop 0
	v_cndmask_b32_e32 v61, v61, v65, vcc
	v_fma_f32 v65, -v63, v69, v67
	v_cmp_ge_f32_e32 vcc, 0, v65
	v_add_u32_e32 v65, 1, v69
	s_nop 0
	v_cndmask_b32_e32 v63, v69, v63, vcc
	v_fma_f32 v69, -v65, v69, v67
	v_cmp_lt_f32_e32 vcc, 0, v69
	v_div_scale_f32 v69, s[40:41], v61, v61, 1.0
	v_rcp_f32_e32 v86, v69
	v_cndmask_b32_e32 v63, v63, v65, vcc
	v_mul_f32_e32 v65, 0x37800000, v63
	v_cndmask_b32_e64 v63, v63, v65, s[8:9]
	v_cmp_class_f32_e32 vcc, v67, v247
	v_fma_f32 v65, -v69, v86, 1.0
	v_fmac_f32_e32 v86, v65, v86
	v_cndmask_b32_e32 v63, v63, v67, vcc
	v_div_scale_f32 v65, vcc, 1.0, v61, 1.0
	v_mul_f32_e32 v67, v65, v86
	v_fma_f32 v87, -v69, v67, v65
	v_fmac_f32_e32 v67, v87, v86
	v_fma_f32 v65, -v69, v67, v65
	v_div_scale_f32 v69, s[8:9], v63, v63, 1.0
	v_rcp_f32_e32 v88, v69
	v_div_fmas_f32 v65, v65, v86, v67
	v_div_fixup_f32 v87, v65, v61, 1.0
	v_fma_f32 v61, -v69, v88, 1.0
	v_fmac_f32_e32 v88, v61, v88
	v_div_scale_f32 v61, vcc, 1.0, v63, 1.0
	v_mul_f32_e32 v65, v61, v88
	v_fma_f32 v67, -v69, v65, v61
	v_fmac_f32_e32 v65, v67, v88
	v_fma_f32 v61, -v69, v65, v61
	v_div_fmas_f32 v61, v61, v88, v65
	v_div_fixup_f32 v86, v61, v63, 1.0
	v_pk_mul_f32 v[84:85], v[84:85], v[86:87]
	v_pk_mul_f32 v[82:83], v[82:83], v[86:87]
	v_pk_fma_f32 v[84:85], v[30:31], v[84:85], v[28:29]
	v_pk_fma_f32 v[82:83], v[6:7], v[82:83], v[2:3]
	v_and_b32_sdwa v61, v85, v242 dst_sel:DWORD dst_unused:UNUSED_PAD src0_sel:WORD_1 src1_sel:DWORD
	v_and_b32_sdwa v63, v84, v242 dst_sel:DWORD dst_unused:UNUSED_PAD src0_sel:WORD_1 src1_sel:DWORD
	v_add3_u32 v63, v84, v63, s80
	v_add3_u32 v61, v85, v61, s80
	v_perm_b32 v61, v61, v63, s81
	v_and_b32_sdwa v63, v83, v242 dst_sel:DWORD dst_unused:UNUSED_PAD src0_sel:WORD_1 src1_sel:DWORD
	v_and_b32_sdwa v65, v82, v242 dst_sel:DWORD dst_unused:UNUSED_PAD src0_sel:WORD_1 src1_sel:DWORD
	v_add3_u32 v65, v82, v65, s80
	v_add3_u32 v63, v83, v63, s80
	v_pk_mul_f32 v[22:23], v[22:23], v[86:87]
	v_perm_b32 v63, v63, v65, s81
	v_pk_fma_f32 v[22:23], v[72:73], v[22:23], v[32:33]
	ds_write2_b32 v0, v61, v63 offset1:68
	v_and_b32_sdwa v61, v23, v242 dst_sel:DWORD dst_unused:UNUSED_PAD src0_sel:WORD_1 src1_sel:DWORD
	v_and_b32_sdwa v63, v22, v242 dst_sel:DWORD dst_unused:UNUSED_PAD src0_sel:WORD_1 src1_sel:DWORD
	v_add3_u32 v22, v22, v63, s80
	v_add3_u32 v23, v23, v61, s80
	v_perm_b32 v61, v23, v22, s81
	v_pk_fma_f32 v[22:23], v[18:19], s[42:43], v[92:93] op_sel_hi:[1,0,1] neg_lo:[1,0,0] neg_hi:[1,0,0]
	s_nop 0
	v_pk_mul_f32 v[22:23], v[22:23], v[86:87]
	s_nop 0
	v_pk_fma_f32 v[22:23], v[8:9], v[22:23], v[4:5]
	s_nop 0
	v_and_b32_sdwa v63, v23, v242 dst_sel:DWORD dst_unused:UNUSED_PAD src0_sel:WORD_1 src1_sel:DWORD
	v_and_b32_sdwa v65, v22, v242 dst_sel:DWORD dst_unused:UNUSED_PAD src0_sel:WORD_1 src1_sel:DWORD
	v_add3_u32 v22, v22, v65, s80
	v_add3_u32 v23, v23, v63, s80
	v_perm_b32 v22, v23, v22, s81
	ds_write2_b32 v0, v61, v22 offset0:136 offset1:204
	v_pk_fma_f32 v[22:23], v[18:19], s[42:43], v[90:91] op_sel_hi:[1,0,1] neg_lo:[1,0,0] neg_hi:[1,0,0]
	s_nop 0
	v_pk_mul_f32 v[22:23], v[22:23], v[86:87]
	s_nop 0
	v_pk_fma_f32 v[22:23], v[76:77], v[22:23], v[74:75]
	s_nop 0
	v_and_b32_sdwa v61, v23, v242 dst_sel:DWORD dst_unused:UNUSED_PAD src0_sel:WORD_1 src1_sel:DWORD
	v_and_b32_sdwa v63, v22, v242 dst_sel:DWORD dst_unused:UNUSED_PAD src0_sel:WORD_1 src1_sel:DWORD
	v_add3_u32 v22, v22, v63, s80
	v_add3_u32 v23, v23, v61, s80
	v_perm_b32 v61, v23, v22, s81
	v_pk_fma_f32 v[22:23], v[18:19], s[42:43], v[94:95] op_sel_hi:[1,0,1] neg_lo:[1,0,0] neg_hi:[1,0,0]
	s_nop 0
	v_pk_mul_f32 v[22:23], v[22:23], v[86:87]
	s_nop 0
	v_pk_fma_f32 v[22:23], v[14:15], v[22:23], v[10:11]
	s_nop 0
	v_and_b32_sdwa v63, v23, v242 dst_sel:DWORD dst_unused:UNUSED_PAD src0_sel:WORD_1 src1_sel:DWORD
	v_and_b32_sdwa v65, v22, v242 dst_sel:DWORD dst_unused:UNUSED_PAD src0_sel:WORD_1 src1_sel:DWORD
	v_add3_u32 v22, v22, v65, s80
	v_add3_u32 v23, v23, v63, s80
	v_perm_b32 v22, v23, v22, s81
	v_add_u32_e32 v63, 0x400, v0
	ds_write2_b32 v63, v61, v22 offset0:16 offset1:84
	v_pk_fma_f32 v[22:23], v[18:19], s[42:43], v[24:25] op_sel_hi:[1,0,1] neg_lo:[1,0,0] neg_hi:[1,0,0]
	v_pk_fma_f32 v[18:19], v[18:19], s[42:43], v[20:21] op_sel_hi:[1,0,1] neg_lo:[1,0,0] neg_hi:[1,0,0]
	v_pk_mul_f32 v[22:23], v[22:23], v[86:87]
	v_pk_mul_f32 v[18:19], v[18:19], v[86:87]
	v_pk_fma_f32 v[22:23], v[80:81], v[22:23], v[78:79]
	v_pk_fma_f32 v[18:19], v[16:17], v[18:19], v[12:13]
	v_and_b32_sdwa v24, v23, v242 dst_sel:DWORD dst_unused:UNUSED_PAD src0_sel:WORD_1 src1_sel:DWORD
	v_and_b32_sdwa v25, v22, v242 dst_sel:DWORD dst_unused:UNUSED_PAD src0_sel:WORD_1 src1_sel:DWORD
	v_and_b32_sdwa v20, v19, v242 dst_sel:DWORD dst_unused:UNUSED_PAD src0_sel:WORD_1 src1_sel:DWORD
	v_and_b32_sdwa v21, v18, v242 dst_sel:DWORD dst_unused:UNUSED_PAD src0_sel:WORD_1 src1_sel:DWORD
	v_add3_u32 v22, v22, v25, s80
	v_add3_u32 v23, v23, v24, s80
	v_add3_u32 v18, v18, v21, s80
	v_add3_u32 v19, v19, v20, s80
	v_perm_b32 v22, v23, v22, s81
	v_perm_b32 v18, v19, v18, s81
	ds_write2_b32 v63, v22, v18 offset0:152 offset1:220
	s_branch .LBB0_661

; __device__ __forceinline__ float bf2f(unsigned short h) { return __uint_as_float(((unsigned)h) << 16); }
; __device__ __forceinline__ unsigned cvtpk(float lo, float hi) { unsigned r; asm volatile("v_cvt_pk_bf16_f32 %0, %1, %2" : "=v"(r) : "v"(lo), "v"(hi)); return r; }
; __device__ __forceinline__ int crow(int r, int hi) { return (r & 3) + 8 * (r >> 2) + 4 * hi; }
; __device__ __forceinline__ void ph_misc(const Args& a, char* lds, int l) {
;     ...
;         for (int ci = 0; ci < 2; ++ci)
; #pragma unroll
;             for (int r = 0; r < 16; ++r) { const int t = 32 * tb + crow(r, hi), c = 32 * (cb0 + ci) + r32; const size_t row = row0 + t;
;                 const float uval = gelu_tanh(bf2f(P[row * NIN + PC_U + g * 128 + c])); const float val = uval * (acc[ci][r] + b_s[l * 512 + g * 128 + t]);
;                 const float vn = __shfl_xor(val, 1); if ((r32 & 1) == 0) *(unsigned*)(MIX + row * DM + 1024 + g * 128 + c) = cvtpk(val, vn); }
.LBB0_672:
	s_lshl_b64 s[0:1], s[34:35], 7
	v_or_b32_e32 v72, s0, v36
	v_mov_b64_e32 v[74:75], s[16:17]
	v_mad_u64_u32 v[74:75], s[6:7], v72, s83, v[74:75]
	v_mad_i32_i24 v75, s1, v244, v75
	s_lshl_b32 s86, s2, 1
	v_lshl_add_u64 v[74:75], v[74:75], 0, s[86:87]
	v_lshl_add_u64 v[74:75], v[38:39], 1, v[74:75]
	v_and_b32_e32 v200, 31, v243
	v_lshrrev_b32_e32 v201, 5, v243
	v_lshlrev_b32_e32 v202, 2, v201
	v_sub_u32_e32 v203, v36, v202
	v_add_u32_e32 v203, v203, v200
	v_or_b32_e32 v203, s0, v203
	v_mov_b64_e32 v[204:205], s[16:17]
	v_mad_u64_u32 v[204:205], s[6:7], v203, s83, v[204:205]
	v_mad_i32_i24 v205, s1, v244, v205
	v_lshl_add_u64 v[204:205], v[204:205], 0, s[86:87]
	v_lshl_add_u64 v[204:205], v[38:39], 1, v[204:205]
	v_lshlrev_b32_e32 v206, 6, v201
	v_add_co_u32_e32 v204, vcc, v204, v206
	s_nop 1
	v_addc_co_u32_e32 v205, vcc, 0, v205, vcc
	v_add_co_u32_e32 v204, vcc, 0x1000, v204
	s_nop 1
	v_addc_co_u32_e32 v205, vcc, 0, v205, vcc
	global_load_dword v207, v[204:205], off offset:512
	v_and_b32_e32 v208, 0xffffffc0, v240
	v_lshlrev_b32_e32 v208, 6, v208
	v_lshl_add_u32 v208, v201, 9, v208
	v_lshl_add_u32 v208, v200, 1, v208
	v_add_u32_e32 v208, 0xa000, v208
	s_movk_i32 s2, 0x1000
	v_add_co_u32_e32 v76, vcc, s2, v74
	v_or_b32_e32 v0, s38, v36
	s_nop 0
	v_addc_co_u32_e32 v77, vcc, 0, v75, vcc
	flat_load_ushort v61, v[76:77] offset:512
	v_lshl_add_u64 v[78:79], v[0:1], 2, s[14:15]
	flat_load_dword v0, v[78:79]
	v_mov_b32_e32 v73, s1
	v_lshlrev_b64 v[72:73], 12, v[72:73]
	v_lshl_add_u64 v[76:77], s[22:23], 0, v[72:73]
	s_waitcnt vmcnt(0) lgkmcnt(0)
	v_lshlrev_b32_e32 v61, 16, v61
	v_mul_f32_e32 v63, 0x3d372713, v61
	v_mul_f32_e32 v63, v63, v61
	v_fma_f32 v63, v63, v61, v61
	v_mul_f32_e32 v63, 0x3f4c422a, v63
	v_mul_f32_e32 v63, 0xc038aa3b, v63
	v_exp_f32_e32 v63, v63
	v_add_f32_e32 v0, v18, v0
	v_add_f32_e32 v63, 1.0, v63
	v_rcp_f32_e32 v63, v63
	s_nop 0
	v_mul_f32_e32 v61, v63, v61
	v_mul_f32_e32 v0, v0, v61
	ds_bpermute_b32 v18, v43, v0
	s_and_saveexec_b64 s[6:7], s[4:5]
	s_cbranch_execz .LBB0_674
	v_lshl_add_u64 v[72:73], v[76:77], 0, s[86:87]
	v_lshl_add_u64 v[72:73], v[38:39], 1, v[72:73]
	v_add_co_u32_e32 v72, vcc, 0x271c0000, v72
	s_waitcnt lgkmcnt(0)
	v_cvt_pk_bf16_f32 v0, v0, v18
	s_nop 0
	v_addc_co_u32_e32 v73, vcc, 0, v73, vcc
	ds_write_b32 v208, v0 offset:0
.LBB0_674:
	s_or_b64 exec, exec, s[6:7]
	s_waitcnt lgkmcnt(0)
	v_or_b32_e32 v18, s0, v40
	v_mov_b64_e32 v[72:73], s[16:17]
	v_mad_u64_u32 v[72:73], s[6:7], v18, s83, v[72:73]
	v_mad_i32_i24 v73, s1, v244, v73
	v_lshl_add_u64 v[72:73], v[72:73], 0, s[86:87]
	v_lshl_add_u64 v[80:81], v[38:39], 1, v[72:73]
	v_add_co_u32_e32 v72, vcc, s2, v80
	v_add_u32_e32 v0, s38, v36
	s_nop 0
	v_addc_co_u32_e32 v73, vcc, 0, v81, vcc
	flat_load_ushort v61, v[72:73] offset:512
	v_lshl_add_u64 v[72:73], v[0:1], 2, s[14:15]
	flat_load_dword v0, v[72:73] offset:4
	s_waitcnt vmcnt(0) lgkmcnt(0)
	v_lshlrev_b32_e32 v61, 16, v61
	v_mul_f32_e32 v63, 0x3d372713, v61
	v_mul_f32_e32 v63, v63, v61
	v_fma_f32 v63, v63, v61, v61
	v_mul_f32_e32 v63, 0x3f4c422a, v63
	v_mul_f32_e32 v63, 0xc038aa3b, v63
	v_exp_f32_e32 v63, v63
	v_add_f32_e32 v0, v19, v0
	v_mov_b32_e32 v19, s1
	v_lshlrev_b64 v[18:19], 12, v[18:19]
	v_add_f32_e32 v63, 1.0, v63
	v_rcp_f32_e32 v63, v63
	v_lshl_add_u64 v[18:19], s[22:23], 0, v[18:19]
	v_mul_f32_e32 v61, v63, v61
	v_mul_f32_e32 v0, v0, v61
	ds_bpermute_b32 v61, v43, v0
	s_and_saveexec_b64 s[6:7], s[4:5]
	s_cbranch_execz .LBB0_676
	v_lshl_add_u64 v[82:83], v[18:19], 0, s[86:87]
	v_lshl_add_u64 v[82:83], v[38:39], 1, v[82:83]
	v_add_co_u32_e32 v82, vcc, 0x271c0000, v82
	s_waitcnt lgkmcnt(0)
	v_cvt_pk_bf16_f32 v0, v0, v61
	s_nop 0
	v_addc_co_u32_e32 v83, vcc, 0, v83, vcc
	ds_write_b32 v208, v0 offset:128
.LBB0_676:
	s_or_b64 exec, exec, s[6:7]
	v_or_b32_e32 v84, s0, v42
	v_mov_b64_e32 v[82:83], s[16:17]
	v_mad_u64_u32 v[82:83], s[6:7], v84, s83, v[82:83]
	v_mad_i32_i24 v83, s1, v244, v83
	v_lshl_add_u64 v[82:83], v[82:83], 0, s[86:87]
	v_lshl_add_u64 v[82:83], v[38:39], 1, v[82:83]
	v_add_co_u32_e32 v86, vcc, s2, v82
	v_mov_b32_e32 v85, s1
	s_nop 0
	v_addc_co_u32_e32 v87, vcc, 0, v83, vcc
	flat_load_ushort v0, v[86:87] offset:512
	s_waitcnt lgkmcnt(0)
	flat_load_dword v61, v[72:73] offset:8
	v_lshlrev_b64 v[84:85], 12, v[84:85]
	v_lshl_add_u64 v[84:85], s[22:23], 0, v[84:85]
	s_waitcnt vmcnt(0)
	v_lshlrev_b32_e32 v0, 16, v0
	v_mul_f32_e32 v63, 0x3d372713, v0
	v_mul_f32_e32 v63, v63, v0
	v_fma_f32 v63, v63, v0, v0
	v_mul_f32_e32 v63, 0x3f4c422a, v63
	v_mul_f32_e32 v63, 0xc038aa3b, v63
	v_exp_f32_e32 v63, v63
	s_waitcnt lgkmcnt(0)
	v_add_f32_e32 v20, v20, v61
	v_add_f32_e32 v63, 1.0, v63
	v_rcp_f32_e32 v63, v63
	s_nop 0
	v_mul_f32_e32 v0, v63, v0
	v_mul_f32_e32 v0, v20, v0
	ds_bpermute_b32 v20, v43, v0
	s_and_saveexec_b64 s[6:7], s[4:5]
	s_cbranch_execz .LBB0_678
	v_lshl_add_u64 v[86:87], v[84:85], 0, s[86:87]
	v_lshl_add_u64 v[86:87], v[38:39], 1, v[86:87]
	v_add_co_u32_e32 v86, vcc, 0x271c0000, v86
	s_waitcnt lgkmcnt(0)
	v_cvt_pk_bf16_f32 v0, v0, v20
	s_nop 0
	v_addc_co_u32_e32 v87, vcc, 0, v87, vcc
	ds_write_b32 v208, v0 offset:256
; __device__ __forceinline__ float bf2f(unsigned short h) { return __uint_as_float(((unsigned)h) << 16); }
; __device__ __forceinline__ unsigned cvtpk(float lo, float hi) { unsigned r; asm volatile("v_cvt_pk_bf16_f32 %0, %1, %2" : "=v"(r) : "v"(lo), "v"(hi)); return r; }
; __device__ __forceinline__ int crow(int r, int hi) { return (r & 3) + 8 * (r >> 2) + 4 * hi; }
; __device__ __forceinline__ void ph_misc(const Args& a, char* lds, int l) {
;     ...
;         for (int ci = 0; ci < 2; ++ci)
; #pragma unroll
;             for (int r = 0; r < 16; ++r) { const int t = 32 * tb + crow(r, hi), c = 32 * (cb0 + ci) + r32; const size_t row = row0 + t;
;                 const float uval = gelu_tanh(bf2f(P[row * NIN + PC_U + g * 128 + c])); const float val = uval * (acc[ci][r] + b_s[l * 512 + g * 128 + t]);
;                 const float vn = __shfl_xor(val, 1); if ((r32 & 1) == 0) *(unsigned*)(MIX + row * DM + 1024 + g * 128 + c) = cvtpk(val, vn); }
.LBB0_678:
	s_or_b64 exec, exec, s[6:7]
	s_waitcnt lgkmcnt(0)
	v_or_b32_e32 v20, s0, v44
	v_mov_b64_e32 v[86:87], s[16:17]
	v_mad_u64_u32 v[86:87], s[6:7], v20, s83, v[86:87]
	v_mad_i32_i24 v87, s1, v244, v87
	v_lshl_add_u64 v[86:87], v[86:87], 0, s[86:87]
	v_lshl_add_u64 v[86:87], v[38:39], 1, v[86:87]
	v_add_co_u32_e32 v88, vcc, s2, v86
	s_nop 1
	v_addc_co_u32_e32 v89, vcc, 0, v87, vcc
	flat_load_ushort v0, v[88:89] offset:512
	flat_load_dword v61, v[72:73] offset:12
	s_waitcnt vmcnt(0) lgkmcnt(0)
	v_lshlrev_b32_e32 v0, 16, v0
	v_mul_f32_e32 v63, 0x3d372713, v0
	v_mul_f32_e32 v63, v63, v0
	v_fma_f32 v63, v63, v0, v0
	v_mul_f32_e32 v63, 0x3f4c422a, v63
	v_mul_f32_e32 v63, 0xc038aa3b, v63
	v_exp_f32_e32 v63, v63
	v_add_f32_e32 v21, v21, v61
	v_add_f32_e32 v63, 1.0, v63
	v_rcp_f32_e32 v63, v63
	s_nop 0
	v_mul_f32_e32 v0, v63, v0
	v_mul_f32_e32 v0, v21, v0
	ds_bpermute_b32 v61, v43, v0
	v_mov_b32_e32 v21, s1
	v_lshlrev_b64 v[20:21], 12, v[20:21]
	v_lshl_add_u64 v[20:21], s[22:23], 0, v[20:21]
	s_and_saveexec_b64 s[6:7], s[4:5]
	s_cbranch_execz .LBB0_680
	v_lshl_add_u64 v[88:89], v[20:21], 0, s[86:87]
	v_lshl_add_u64 v[88:89], v[38:39], 1, v[88:89]
	v_add_co_u32_e32 v88, vcc, 0x271c0000, v88
	s_waitcnt lgkmcnt(0)
	v_cvt_pk_bf16_f32 v0, v0, v61
	s_nop 0
	v_addc_co_u32_e32 v89, vcc, 0, v89, vcc
	ds_write_b32 v208, v0 offset:384
.LBB0_680:
	s_or_b64 exec, exec, s[6:7]
	v_or_b32_e32 v90, s0, v46
	v_mov_b64_e32 v[88:89], s[16:17]
	v_mad_u64_u32 v[88:89], s[6:7], v90, s83, v[88:89]
	v_mad_i32_i24 v89, s1, v244, v89
	v_lshl_add_u64 v[88:89], v[88:89], 0, s[86:87]
	v_lshl_add_u64 v[88:89], v[38:39], 1, v[88:89]
	v_add_co_u32_e32 v92, vcc, s2, v88
	v_mov_b32_e32 v91, s1
	s_nop 0
	v_addc_co_u32_e32 v93, vcc, 0, v89, vcc
	flat_load_ushort v0, v[92:93] offset:512
	s_waitcnt lgkmcnt(0)
	flat_load_dword v61, v[72:73] offset:32
	v_lshlrev_b64 v[90:91], 12, v[90:91]
	v_lshl_add_u64 v[90:91], s[22:23], 0, v[90:91]
	s_waitcnt vmcnt(0)
	v_lshlrev_b32_e32 v0, 16, v0
	v_mul_f32_e32 v63, 0x3d372713, v0
	v_mul_f32_e32 v63, v63, v0
	v_fma_f32 v63, v63, v0, v0
	v_mul_f32_e32 v63, 0x3f4c422a, v63
	v_mul_f32_e32 v63, 0xc038aa3b, v63
	v_exp_f32_e32 v63, v63
	s_waitcnt lgkmcnt(0)
	v_add_f32_e32 v22, v22, v61
	v_add_f32_e32 v63, 1.0, v63
	v_rcp_f32_e32 v63, v63
	s_nop 0
	v_mul_f32_e32 v0, v63, v0
	v_mul_f32_e32 v0, v22, v0
	ds_bpermute_b32 v22, v43, v0
	s_and_saveexec_b64 s[6:7], s[4:5]
	s_cbranch_execz .LBB0_682
	v_lshl_add_u64 v[92:93], v[90:91], 0, s[86:87]
	v_lshl_add_u64 v[92:93], v[38:39], 1, v[92:93]
	v_add_co_u32_e32 v92, vcc, 0x271c0000, v92
	s_waitcnt lgkmcnt(0)
	v_cvt_pk_bf16_f32 v0, v0, v22
	s_nop 0
	v_addc_co_u32_e32 v93, vcc, 0, v93, vcc
	ds_write_b32 v208, v0 offset:1024
.LBB0_682:
	s_or_b64 exec, exec, s[6:7]
	s_waitcnt lgkmcnt(0)
	v_or_b32_e32 v22, s0, v48
	v_mov_b64_e32 v[92:93], s[16:17]
	v_mad_u64_u32 v[92:93], s[6:7], v22, s83, v[92:93]
	v_mad_i32_i24 v93, s1, v244, v93
	v_lshl_add_u64 v[92:93], v[92:93], 0, s[86:87]
	v_lshl_add_u64 v[92:93], v[38:39], 1, v[92:93]
	v_add_co_u32_e32 v94, vcc, s2, v92
	s_nop 1
	v_addc_co_u32_e32 v95, vcc, 0, v93, vcc
	flat_load_ushort v0, v[94:95] offset:512
	flat_load_dword v61, v[72:73] offset:36
	s_waitcnt vmcnt(0) lgkmcnt(0)
	v_lshlrev_b32_e32 v0, 16, v0
	v_mul_f32_e32 v63, 0x3d372713, v0
	v_mul_f32_e32 v63, v63, v0
	v_fma_f32 v63, v63, v0, v0
	v_mul_f32_e32 v63, 0x3f4c422a, v63
	v_mul_f32_e32 v63, 0xc038aa3b, v63
	v_exp_f32_e32 v63, v63
	v_add_f32_e32 v23, v23, v61
	v_add_f32_e32 v63, 1.0, v63
	v_rcp_f32_e32 v63, v63
	s_nop 0
	v_mul_f32_e32 v0, v63, v0
	v_mul_f32_e32 v0, v23, v0
	ds_bpermute_b32 v61, v43, v0
	v_mov_b32_e32 v23, s1
	v_lshlrev_b64 v[22:23], 12, v[22:23]
	v_lshl_add_u64 v[22:23], s[22:23], 0, v[22:23]
	s_and_saveexec_b64 s[6:7], s[4:5]
	s_cbranch_execz .LBB0_684
	v_lshl_add_u64 v[94:95], v[22:23], 0, s[86:87]
	v_lshl_add_u64 v[94:95], v[38:39], 1, v[94:95]
	v_add_co_u32_e32 v94, vcc, 0x271c0000, v94
	s_waitcnt lgkmcnt(0)
	v_cvt_pk_bf16_f32 v0, v0, v61
	s_nop 0
	v_addc_co_u32_e32 v95, vcc, 0, v95, vcc
	ds_write_b32 v208, v0 offset:1152
.LBB0_684:
	s_or_b64 exec, exec, s[6:7]
	v_or_b32_e32 v96, s0, v50
	v_mov_b64_e32 v[94:95], s[16:17]
	v_mad_u64_u32 v[94:95], s[6:7], v96, s83, v[94:95]
	v_mad_i32_i24 v95, s1, v244, v95
	v_lshl_add_u64 v[94:95], v[94:95], 0, s[86:87]
	v_lshl_add_u64 v[94:95], v[38:39], 1, v[94:95]
	v_add_co_u32_e32 v98, vcc, s2, v94
	v_mov_b32_e32 v97, s1
	s_nop 0
	v_addc_co_u32_e32 v99, vcc, 0, v95, vcc
	flat_load_ushort v0, v[98:99] offset:512
	s_waitcnt lgkmcnt(0)
	flat_load_dword v61, v[72:73] offset:40
	v_lshlrev_b64 v[96:97], 12, v[96:97]
	v_lshl_add_u64 v[96:97], s[22:23], 0, v[96:97]
	s_waitcnt vmcnt(0)
	v_lshlrev_b32_e32 v0, 16, v0
	v_mul_f32_e32 v63, 0x3d372713, v0
	v_mul_f32_e32 v63, v63, v0
	v_fma_f32 v63, v63, v0, v0
	v_mul_f32_e32 v63, 0x3f4c422a, v63
	v_mul_f32_e32 v63, 0xc038aa3b, v63
	v_exp_f32_e32 v63, v63
	s_waitcnt lgkmcnt(0)
	v_add_f32_e32 v24, v24, v61
	v_add_f32_e32 v63, 1.0, v63
	v_rcp_f32_e32 v63, v63
	s_nop 0
	v_mul_f32_e32 v0, v63, v0
	v_mul_f32_e32 v0, v24, v0
	ds_bpermute_b32 v24, v43, v0
	s_and_saveexec_b64 s[6:7], s[4:5]
	s_cbranch_execz .LBB0_686
	v_lshl_add_u64 v[98:99], v[96:97], 0, s[86:87]
	v_lshl_add_u64 v[98:99], v[38:39], 1, v[98:99]
	v_add_co_u32_e32 v98, vcc, 0x271c0000, v98
	s_waitcnt lgkmcnt(0)
	v_cvt_pk_bf16_f32 v0, v0, v24
	s_nop 0
	v_addc_co_u32_e32 v99, vcc, 0, v99, vcc
	ds_write_b32 v208, v0 offset:1280
; __device__ __forceinline__ float bf2f(unsigned short h) { return __uint_as_float(((unsigned)h) << 16); }
; __device__ __forceinline__ unsigned cvtpk(float lo, float hi) { unsigned r; asm volatile("v_cvt_pk_bf16_f32 %0, %1, %2" : "=v"(r) : "v"(lo), "v"(hi)); return r; }
; __device__ __forceinline__ int crow(int r, int hi) { return (r & 3) + 8 * (r >> 2) + 4 * hi; }
; __device__ __forceinline__ void ph_misc(const Args& a, char* lds, int l) {
;     ...
;         for (int ci = 0; ci < 2; ++ci)
; #pragma unroll
;             for (int r = 0; r < 16; ++r) { const int t = 32 * tb + crow(r, hi), c = 32 * (cb0 + ci) + r32; const size_t row = row0 + t;
;                 const float uval = gelu_tanh(bf2f(P[row * NIN + PC_U + g * 128 + c])); const float val = uval * (acc[ci][r] + b_s[l * 512 + g * 128 + t]);
;                 const float vn = __shfl_xor(val, 1); if ((r32 & 1) == 0) *(unsigned*)(MIX + row * DM + 1024 + g * 128 + c) = cvtpk(val, vn); }
.LBB0_686:
	s_or_b64 exec, exec, s[6:7]
	s_waitcnt lgkmcnt(0)
	v_or_b32_e32 v24, s0, v52
	v_mov_b64_e32 v[98:99], s[16:17]
	v_mad_u64_u32 v[98:99], s[6:7], v24, s83, v[98:99]
	v_mad_i32_i24 v99, s1, v244, v99
	v_lshl_add_u64 v[98:99], v[98:99], 0, s[86:87]
	v_lshl_add_u64 v[98:99], v[38:39], 1, v[98:99]
	v_add_co_u32_e32 v100, vcc, s2, v98
	s_nop 1
	v_addc_co_u32_e32 v101, vcc, 0, v99, vcc
	flat_load_ushort v0, v[100:101] offset:512
	flat_load_dword v61, v[72:73] offset:44
	s_waitcnt vmcnt(0) lgkmcnt(0)
	v_lshlrev_b32_e32 v0, 16, v0
	v_mul_f32_e32 v63, 0x3d372713, v0
	v_mul_f32_e32 v63, v63, v0
	v_fma_f32 v63, v63, v0, v0
	v_mul_f32_e32 v63, 0x3f4c422a, v63
	v_mul_f32_e32 v63, 0xc038aa3b, v63
	v_exp_f32_e32 v63, v63
	v_add_f32_e32 v25, v25, v61
	v_add_f32_e32 v63, 1.0, v63
	v_rcp_f32_e32 v63, v63
	s_nop 0
	v_mul_f32_e32 v0, v63, v0
	v_mul_f32_e32 v0, v25, v0
	ds_bpermute_b32 v61, v43, v0
	v_mov_b32_e32 v25, s1
	v_lshlrev_b64 v[24:25], 12, v[24:25]
	v_lshl_add_u64 v[24:25], s[22:23], 0, v[24:25]
	s_and_saveexec_b64 s[6:7], s[4:5]
	s_cbranch_execz .LBB0_688
	v_lshl_add_u64 v[100:101], v[24:25], 0, s[86:87]
	v_lshl_add_u64 v[100:101], v[38:39], 1, v[100:101]
	v_add_co_u32_e32 v100, vcc, 0x271c0000, v100
	s_waitcnt lgkmcnt(0)
	v_cvt_pk_bf16_f32 v0, v0, v61
	s_nop 0
	v_addc_co_u32_e32 v101, vcc, 0, v101, vcc
	ds_write_b32 v208, v0 offset:1408
.LBB0_688:
	s_or_b64 exec, exec, s[6:7]
	v_or_b32_e32 v102, s0, v54
	v_mov_b64_e32 v[100:101], s[16:17]
	v_mad_u64_u32 v[100:101], s[6:7], v102, s83, v[100:101]
	v_mad_i32_i24 v101, s1, v244, v101
	v_lshl_add_u64 v[100:101], v[100:101], 0, s[86:87]
	v_lshl_add_u64 v[100:101], v[38:39], 1, v[100:101]
	v_add_co_u32_e32 v104, vcc, s2, v100
	v_mov_b32_e32 v103, s1
	s_nop 0
	v_addc_co_u32_e32 v105, vcc, 0, v101, vcc
	flat_load_ushort v0, v[104:105] offset:512
	s_waitcnt lgkmcnt(0)
	flat_load_dword v61, v[72:73] offset:64
	v_lshlrev_b64 v[102:103], 12, v[102:103]
	v_lshl_add_u64 v[102:103], s[22:23], 0, v[102:103]
	s_waitcnt vmcnt(0)
	v_lshlrev_b32_e32 v0, 16, v0
	v_mul_f32_e32 v63, 0x3d372713, v0
	v_mul_f32_e32 v63, v63, v0
	v_fma_f32 v63, v63, v0, v0
	v_mul_f32_e32 v63, 0x3f4c422a, v63
	v_mul_f32_e32 v63, 0xc038aa3b, v63
	v_exp_f32_e32 v63, v63
	s_waitcnt lgkmcnt(0)
	v_add_f32_e32 v26, v26, v61
	v_add_f32_e32 v63, 1.0, v63
	v_rcp_f32_e32 v63, v63
	s_nop 0
	v_mul_f32_e32 v0, v63, v0
	v_mul_f32_e32 v0, v26, v0
	ds_bpermute_b32 v26, v43, v0
	s_and_saveexec_b64 s[6:7], s[4:5]
	s_cbranch_execz .LBB0_690
	v_lshl_add_u64 v[104:105], v[102:103], 0, s[86:87]
	v_lshl_add_u64 v[104:105], v[38:39], 1, v[104:105]
	v_add_co_u32_e32 v104, vcc, 0x271c0000, v104
	s_waitcnt lgkmcnt(0)
	v_cvt_pk_bf16_f32 v0, v0, v26
	s_nop 0
	v_addc_co_u32_e32 v105, vcc, 0, v105, vcc
	ds_write_b32 v208, v0 offset:2048
.LBB0_690:
	s_or_b64 exec, exec, s[6:7]
	s_waitcnt lgkmcnt(0)
	v_or_b32_e32 v26, s0, v56
	v_mov_b64_e32 v[104:105], s[16:17]
	v_mad_u64_u32 v[104:105], s[6:7], v26, s83, v[104:105]
	v_mad_i32_i24 v105, s1, v244, v105
	v_lshl_add_u64 v[104:105], v[104:105], 0, s[86:87]
	v_lshl_add_u64 v[104:105], v[38:39], 1, v[104:105]
	v_add_co_u32_e32 v106, vcc, s2, v104
	s_nop 1
	v_addc_co_u32_e32 v107, vcc, 0, v105, vcc
	flat_load_ushort v0, v[106:107] offset:512
	flat_load_dword v61, v[72:73] offset:68
	s_waitcnt vmcnt(0) lgkmcnt(0)
	v_lshlrev_b32_e32 v0, 16, v0
	v_mul_f32_e32 v63, 0x3d372713, v0
	v_mul_f32_e32 v63, v63, v0
	v_fma_f32 v63, v63, v0, v0
	v_mul_f32_e32 v63, 0x3f4c422a, v63
	v_mul_f32_e32 v63, 0xc038aa3b, v63
	v_exp_f32_e32 v63, v63
	v_add_f32_e32 v27, v27, v61
	v_add_f32_e32 v63, 1.0, v63
	v_rcp_f32_e32 v63, v63
	s_nop 0
	v_mul_f32_e32 v0, v63, v0
	v_mul_f32_e32 v0, v27, v0
	ds_bpermute_b32 v61, v43, v0
	v_mov_b32_e32 v27, s1
	v_lshlrev_b64 v[26:27], 12, v[26:27]
	v_lshl_add_u64 v[26:27], s[22:23], 0, v[26:27]
	s_and_saveexec_b64 s[6:7], s[4:5]
	s_cbranch_execz .LBB0_692
	v_lshl_add_u64 v[106:107], v[26:27], 0, s[86:87]
	v_lshl_add_u64 v[106:107], v[38:39], 1, v[106:107]
	v_add_co_u32_e32 v106, vcc, 0x271c0000, v106
	s_waitcnt lgkmcnt(0)
	v_cvt_pk_bf16_f32 v0, v0, v61
	s_nop 0
	v_addc_co_u32_e32 v107, vcc, 0, v107, vcc
	ds_write_b32 v208, v0 offset:2176
.LBB0_692:
	s_or_b64 exec, exec, s[6:7]
	v_or_b32_e32 v108, s0, v58
	v_mov_b64_e32 v[106:107], s[16:17]
	v_mad_u64_u32 v[106:107], s[6:7], v108, s83, v[106:107]
	v_mad_i32_i24 v107, s1, v244, v107
	v_lshl_add_u64 v[106:107], v[106:107], 0, s[86:87]
	v_lshl_add_u64 v[106:107], v[38:39], 1, v[106:107]
	v_add_co_u32_e32 v110, vcc, s2, v106
	v_mov_b32_e32 v109, s1
	s_nop 0
	v_addc_co_u32_e32 v111, vcc, 0, v107, vcc
	flat_load_ushort v0, v[110:111] offset:512
	s_waitcnt lgkmcnt(0)
	flat_load_dword v61, v[72:73] offset:72
	v_lshlrev_b64 v[108:109], 12, v[108:109]
	v_lshl_add_u64 v[108:109], s[22:23], 0, v[108:109]
	s_waitcnt vmcnt(0)
	v_lshlrev_b32_e32 v0, 16, v0
	v_mul_f32_e32 v63, 0x3d372713, v0
	v_mul_f32_e32 v63, v63, v0
	v_fma_f32 v63, v63, v0, v0
	v_mul_f32_e32 v63, 0x3f4c422a, v63
	v_mul_f32_e32 v63, 0xc038aa3b, v63
	v_exp_f32_e32 v63, v63
	s_waitcnt lgkmcnt(0)
	v_add_f32_e32 v28, v28, v61
	v_add_f32_e32 v63, 1.0, v63
	v_rcp_f32_e32 v63, v63
	s_nop 0
	v_mul_f32_e32 v0, v63, v0
	v_mul_f32_e32 v0, v28, v0
	ds_bpermute_b32 v28, v43, v0
	s_and_saveexec_b64 s[6:7], s[4:5]
	s_cbranch_execz .LBB0_694
	v_lshl_add_u64 v[110:111], v[108:109], 0, s[86:87]
	v_lshl_add_u64 v[110:111], v[38:39], 1, v[110:111]
	v_add_co_u32_e32 v110, vcc, 0x271c0000, v110
	s_waitcnt lgkmcnt(0)
	v_cvt_pk_bf16_f32 v0, v0, v28
	s_nop 0
	v_addc_co_u32_e32 v111, vcc, 0, v111, vcc
	ds_write_b32 v208, v0 offset:2304
; __device__ __forceinline__ float bf2f(unsigned short h) { return __uint_as_float(((unsigned)h) << 16); }
; __device__ __forceinline__ unsigned cvtpk(float lo, float hi) { unsigned r; asm volatile("v_cvt_pk_bf16_f32 %0, %1, %2" : "=v"(r) : "v"(lo), "v"(hi)); return r; }
; __device__ __forceinline__ int crow(int r, int hi) { return (r & 3) + 8 * (r >> 2) + 4 * hi; }
; __device__ __forceinline__ void ph_misc(const Args& a, char* lds, int l) {
;     ...
;         for (int ci = 0; ci < 2; ++ci)
; #pragma unroll
;             for (int r = 0; r < 16; ++r) { const int t = 32 * tb + crow(r, hi), c = 32 * (cb0 + ci) + r32; const size_t row = row0 + t;
;                 const float uval = gelu_tanh(bf2f(P[row * NIN + PC_U + g * 128 + c])); const float val = uval * (acc[ci][r] + b_s[l * 512 + g * 128 + t]);
;                 const float vn = __shfl_xor(val, 1); if ((r32 & 1) == 0) *(unsigned*)(MIX + row * DM + 1024 + g * 128 + c) = cvtpk(val, vn); }
.LBB0_694:
	s_or_b64 exec, exec, s[6:7]
	s_waitcnt lgkmcnt(0)
	v_or_b32_e32 v28, s0, v60
	v_mov_b64_e32 v[110:111], s[16:17]
	v_mad_u64_u32 v[110:111], s[6:7], v28, s83, v[110:111]
	v_mad_i32_i24 v111, s1, v244, v111
	v_lshl_add_u64 v[110:111], v[110:111], 0, s[86:87]
	v_lshl_add_u64 v[110:111], v[38:39], 1, v[110:111]
	v_add_co_u32_e32 v112, vcc, s2, v110
	s_nop 1
	v_addc_co_u32_e32 v113, vcc, 0, v111, vcc
	flat_load_ushort v0, v[112:113] offset:512
	flat_load_dword v61, v[72:73] offset:76
	s_waitcnt vmcnt(0) lgkmcnt(0)
	v_lshlrev_b32_e32 v0, 16, v0
	v_mul_f32_e32 v63, 0x3d372713, v0
	v_mul_f32_e32 v63, v63, v0
	v_fma_f32 v63, v63, v0, v0
	v_mul_f32_e32 v63, 0x3f4c422a, v63
	v_mul_f32_e32 v63, 0xc038aa3b, v63
	v_exp_f32_e32 v63, v63
	v_add_f32_e32 v29, v29, v61
	v_add_f32_e32 v63, 1.0, v63
	v_rcp_f32_e32 v63, v63
	s_nop 0
	v_mul_f32_e32 v0, v63, v0
	v_mul_f32_e32 v0, v29, v0
	ds_bpermute_b32 v61, v43, v0
	v_mov_b32_e32 v29, s1
	v_lshlrev_b64 v[28:29], 12, v[28:29]
	v_lshl_add_u64 v[28:29], s[22:23], 0, v[28:29]
	s_and_saveexec_b64 s[6:7], s[4:5]
	s_cbranch_execz .LBB0_696
	v_lshl_add_u64 v[112:113], v[28:29], 0, s[86:87]
	v_lshl_add_u64 v[112:113], v[38:39], 1, v[112:113]
	v_add_co_u32_e32 v112, vcc, 0x271c0000, v112
	s_waitcnt lgkmcnt(0)
	v_cvt_pk_bf16_f32 v0, v0, v61
	s_nop 0
	v_addc_co_u32_e32 v113, vcc, 0, v113, vcc
	ds_write_b32 v208, v0 offset:2432
.LBB0_696:
	s_or_b64 exec, exec, s[6:7]
	v_or_b32_e32 v114, s0, v62
	v_mov_b64_e32 v[112:113], s[16:17]
	v_mad_u64_u32 v[112:113], s[6:7], v114, s83, v[112:113]
	v_mad_i32_i24 v113, s1, v244, v113
	v_lshl_add_u64 v[112:113], v[112:113], 0, s[86:87]
	v_lshl_add_u64 v[112:113], v[38:39], 1, v[112:113]
	v_add_co_u32_e32 v116, vcc, s2, v112
	v_mov_b32_e32 v115, s1
	s_nop 0
	v_addc_co_u32_e32 v117, vcc, 0, v113, vcc
	flat_load_ushort v0, v[116:117] offset:512
	s_waitcnt lgkmcnt(0)
	flat_load_dword v61, v[72:73] offset:96
	v_lshlrev_b64 v[114:115], 12, v[114:115]
	v_lshl_add_u64 v[114:115], s[22:23], 0, v[114:115]
	s_waitcnt vmcnt(0)
	v_lshlrev_b32_e32 v0, 16, v0
	v_mul_f32_e32 v63, 0x3d372713, v0
	v_mul_f32_e32 v63, v63, v0
	v_fma_f32 v63, v63, v0, v0
	v_mul_f32_e32 v63, 0x3f4c422a, v63
	v_mul_f32_e32 v63, 0xc038aa3b, v63
	v_exp_f32_e32 v63, v63
	s_waitcnt lgkmcnt(0)
	v_add_f32_e32 v30, v30, v61
	v_add_f32_e32 v63, 1.0, v63
	v_rcp_f32_e32 v63, v63
	s_nop 0
	v_mul_f32_e32 v0, v63, v0
	v_mul_f32_e32 v0, v30, v0
	ds_bpermute_b32 v30, v43, v0
	s_and_saveexec_b64 s[6:7], s[4:5]
	s_cbranch_execz .LBB0_698
	v_lshl_add_u64 v[116:117], v[114:115], 0, s[86:87]
	v_lshl_add_u64 v[116:117], v[38:39], 1, v[116:117]
	v_add_co_u32_e32 v116, vcc, 0x271c0000, v116
	s_waitcnt lgkmcnt(0)
	v_cvt_pk_bf16_f32 v0, v0, v30
	s_nop 0
	v_addc_co_u32_e32 v117, vcc, 0, v117, vcc
	ds_write_b32 v208, v0 offset:3072
.LBB0_698:
	s_or_b64 exec, exec, s[6:7]
	s_waitcnt lgkmcnt(0)
	v_or_b32_e32 v30, s0, v64
	v_mov_b64_e32 v[116:117], s[16:17]
	v_mad_u64_u32 v[116:117], s[6:7], v30, s83, v[116:117]
	v_mad_i32_i24 v117, s1, v244, v117
	v_lshl_add_u64 v[116:117], v[116:117], 0, s[86:87]
	v_lshl_add_u64 v[116:117], v[38:39], 1, v[116:117]
	v_add_co_u32_e32 v118, vcc, s2, v116
	s_nop 1
	v_addc_co_u32_e32 v119, vcc, 0, v117, vcc
	flat_load_ushort v0, v[118:119] offset:512
	flat_load_dword v61, v[72:73] offset:100
	s_waitcnt vmcnt(0) lgkmcnt(0)
	v_lshlrev_b32_e32 v0, 16, v0
	v_mul_f32_e32 v63, 0x3d372713, v0
	v_mul_f32_e32 v63, v63, v0
	v_fma_f32 v63, v63, v0, v0
	v_mul_f32_e32 v63, 0x3f4c422a, v63
	v_mul_f32_e32 v63, 0xc038aa3b, v63
	v_exp_f32_e32 v63, v63
	v_add_f32_e32 v31, v31, v61
	v_add_f32_e32 v63, 1.0, v63
	v_rcp_f32_e32 v63, v63
	s_nop 0
	v_mul_f32_e32 v0, v63, v0
	v_mul_f32_e32 v0, v31, v0
	ds_bpermute_b32 v61, v43, v0
	v_mov_b32_e32 v31, s1
	v_lshlrev_b64 v[30:31], 12, v[30:31]
	v_lshl_add_u64 v[30:31], s[22:23], 0, v[30:31]
	s_and_saveexec_b64 s[6:7], s[4:5]
	s_cbranch_execz .LBB0_700
	v_lshl_add_u64 v[118:119], v[30:31], 0, s[86:87]
	v_lshl_add_u64 v[118:119], v[38:39], 1, v[118:119]
	v_add_co_u32_e32 v118, vcc, 0x271c0000, v118
	s_waitcnt lgkmcnt(0)
	v_cvt_pk_bf16_f32 v0, v0, v61
	s_nop 0
	v_addc_co_u32_e32 v119, vcc, 0, v119, vcc
	ds_write_b32 v208, v0 offset:3200
.LBB0_700:
	s_or_b64 exec, exec, s[6:7]
	v_or_b32_e32 v120, s0, v66
	v_mov_b64_e32 v[118:119], s[16:17]
	v_mad_u64_u32 v[118:119], s[6:7], v120, s83, v[118:119]
	v_mad_i32_i24 v119, s1, v244, v119
	v_lshl_add_u64 v[118:119], v[118:119], 0, s[86:87]
	v_lshl_add_u64 v[118:119], v[38:39], 1, v[118:119]
	v_add_co_u32_e32 v122, vcc, s2, v118
	v_mov_b32_e32 v121, s1
	s_nop 0
	v_addc_co_u32_e32 v123, vcc, 0, v119, vcc
	flat_load_ushort v0, v[122:123] offset:512
	s_waitcnt lgkmcnt(0)
	flat_load_dword v61, v[72:73] offset:104
	v_lshlrev_b64 v[120:121], 12, v[120:121]
	v_lshl_add_u64 v[120:121], s[22:23], 0, v[120:121]
	s_waitcnt vmcnt(0)
	v_lshlrev_b32_e32 v0, 16, v0
	v_mul_f32_e32 v63, 0x3d372713, v0
	v_mul_f32_e32 v63, v63, v0
	v_fma_f32 v63, v63, v0, v0
	v_mul_f32_e32 v63, 0x3f4c422a, v63
	v_mul_f32_e32 v63, 0xc038aa3b, v63
	v_exp_f32_e32 v63, v63
	s_waitcnt lgkmcnt(0)
	v_add_f32_e32 v32, v32, v61
	v_add_f32_e32 v63, 1.0, v63
	v_rcp_f32_e32 v63, v63
	s_nop 0
	v_mul_f32_e32 v0, v63, v0
	v_mul_f32_e32 v0, v32, v0
	ds_bpermute_b32 v32, v43, v0
	s_and_saveexec_b64 s[6:7], s[4:5]
	s_cbranch_execz .LBB0_702
	v_lshl_add_u64 v[122:123], v[120:121], 0, s[86:87]
	v_lshl_add_u64 v[122:123], v[38:39], 1, v[122:123]
	v_add_co_u32_e32 v122, vcc, 0x271c0000, v122
	s_waitcnt lgkmcnt(0)
	v_cvt_pk_bf16_f32 v0, v0, v32
	s_nop 0
	v_addc_co_u32_e32 v123, vcc, 0, v123, vcc
	ds_write_b32 v208, v0 offset:3328
; __device__ __forceinline__ float bf2f(unsigned short h) { return __uint_as_float(((unsigned)h) << 16); }
; __device__ __forceinline__ unsigned cvtpk(float lo, float hi) { unsigned r; asm volatile("v_cvt_pk_bf16_f32 %0, %1, %2" : "=v"(r) : "v"(lo), "v"(hi)); return r; }
; __device__ __forceinline__ int crow(int r, int hi) { return (r & 3) + 8 * (r >> 2) + 4 * hi; }
; __device__ __forceinline__ void ph_misc(const Args& a, char* lds, int l) {
;     ...
;         for (int ci = 0; ci < 2; ++ci)
; #pragma unroll
;             for (int r = 0; r < 16; ++r) { const int t = 32 * tb + crow(r, hi), c = 32 * (cb0 + ci) + r32; const size_t row = row0 + t;
;                 const float uval = gelu_tanh(bf2f(P[row * NIN + PC_U + g * 128 + c])); const float val = uval * (acc[ci][r] + b_s[l * 512 + g * 128 + t]);
;                 const float vn = __shfl_xor(val, 1); if ((r32 & 1) == 0) *(unsigned*)(MIX + row * DM + 1024 + g * 128 + c) = cvtpk(val, vn); }
.LBB0_702:
	s_or_b64 exec, exec, s[6:7]
	s_waitcnt lgkmcnt(0)
	v_or_b32_e32 v32, s0, v68
	v_mov_b64_e32 v[122:123], s[16:17]
	v_mad_u64_u32 v[122:123], s[6:7], v32, s83, v[122:123]
	v_mad_i32_i24 v123, s1, v244, v123
	v_lshl_add_u64 v[122:123], v[122:123], 0, s[86:87]
	v_lshl_add_u64 v[122:123], v[38:39], 1, v[122:123]
	s_movk_i32 s0, 0x1000
	v_add_co_u32_e32 v124, vcc, s0, v122
	s_nop 1
	v_addc_co_u32_e32 v125, vcc, 0, v123, vcc
	flat_load_ushort v0, v[124:125] offset:512
	flat_load_dword v61, v[72:73] offset:108
	s_waitcnt vmcnt(0) lgkmcnt(0)
	v_lshlrev_b32_e32 v0, 16, v0
	v_mul_f32_e32 v63, 0x3d372713, v0
	v_mul_f32_e32 v63, v63, v0
	v_fma_f32 v63, v63, v0, v0
	v_mul_f32_e32 v63, 0x3f4c422a, v63
	v_mul_f32_e32 v63, 0xc038aa3b, v63
	v_exp_f32_e32 v63, v63
	v_add_f32_e32 v33, v33, v61
	v_add_f32_e32 v63, 1.0, v63
	v_rcp_f32_e32 v63, v63
	s_nop 0
	v_mul_f32_e32 v0, v63, v0
	v_mul_f32_e32 v0, v33, v0
	ds_bpermute_b32 v61, v43, v0
	v_mov_b32_e32 v33, s1
	v_lshlrev_b64 v[32:33], 12, v[32:33]
	v_lshl_add_u64 v[32:33], s[22:23], 0, v[32:33]
	s_and_saveexec_b64 s[0:1], s[4:5]
	s_cbranch_execz .LBB0_704
	v_lshl_add_u64 v[124:125], v[32:33], 0, s[86:87]
	v_lshl_add_u64 v[124:125], v[38:39], 1, v[124:125]
	v_add_co_u32_e32 v124, vcc, 0x271c0000, v124
	s_waitcnt lgkmcnt(0)
	v_cvt_pk_bf16_f32 v0, v0, v61
	s_nop 0
	v_addc_co_u32_e32 v125, vcc, 0, v125, vcc
	ds_write_b32 v208, v0 offset:3456
.LBB0_704:
	s_or_b64 exec, exec, s[0:1]
	s_mov_b64 s[0:1], 0x1200
	v_lshl_add_u64 v[74:75], v[74:75], 0, s[0:1]
	flat_load_ushort v0, v[74:75] offset:64
	s_waitcnt lgkmcnt(0)
	flat_load_dword v61, v[78:79]
	s_waitcnt vmcnt(0)
	v_lshlrev_b32_e32 v0, 16, v0
	v_mul_f32_e32 v63, 0x3d372713, v0
	v_mul_f32_e32 v63, v63, v0
	v_fma_f32 v63, v63, v0, v0
	v_mul_f32_e32 v63, 0x3f4c422a, v63
	v_mul_f32_e32 v63, 0xc038aa3b, v63
	v_exp_f32_e32 v63, v63
	s_waitcnt lgkmcnt(0)
	v_add_f32_e32 v2, v2, v61
	v_add_f32_e32 v63, 1.0, v63
	v_rcp_f32_e32 v63, v63
	s_nop 0
	v_mul_f32_e32 v0, v63, v0
	v_mul_f32_e32 v0, v2, v0
	ds_bpermute_b32 v2, v43, v0
	s_and_saveexec_b64 s[0:1], s[4:5]
	s_cbranch_execz .LBB0_706
	v_lshl_add_u64 v[74:75], v[76:77], 0, s[86:87]
	v_lshl_add_u64 v[74:75], v[38:39], 1, v[74:75]
	v_add_co_u32_e32 v74, vcc, 0x271c0000, v74
	s_waitcnt lgkmcnt(0)
	v_cvt_pk_bf16_f32 v0, v0, v2
	s_nop 0
	v_addc_co_u32_e32 v75, vcc, 0, v75, vcc
	ds_write_b32 v208, v0 offset:64
.LBB0_706:
	s_or_b64 exec, exec, s[0:1]
	s_mov_b64 s[0:1], 0x1200
	v_lshl_add_u64 v[74:75], v[80:81], 0, s[0:1]
	flat_load_ushort v0, v[74:75] offset:64
	s_waitcnt lgkmcnt(0)
	flat_load_dword v2, v[72:73] offset:4
	s_waitcnt vmcnt(0)
	v_lshlrev_b32_e32 v0, 16, v0
	v_mul_f32_e32 v61, 0x3d372713, v0
	v_mul_f32_e32 v61, v61, v0
	v_fma_f32 v61, v61, v0, v0
	v_mul_f32_e32 v61, 0x3f4c422a, v61
	v_mul_f32_e32 v61, 0xc038aa3b, v61
	v_exp_f32_e32 v61, v61
	s_waitcnt lgkmcnt(0)
	v_add_f32_e32 v2, v3, v2
	v_add_f32_e32 v61, 1.0, v61
	v_rcp_f32_e32 v61, v61
	s_nop 0
	v_mul_f32_e32 v0, v61, v0
	v_mul_f32_e32 v0, v2, v0
	ds_bpermute_b32 v2, v43, v0
	s_and_saveexec_b64 s[0:1], s[4:5]
	s_cbranch_execz .LBB0_708
	v_lshl_add_u64 v[18:19], v[18:19], 0, s[86:87]
	v_lshl_add_u64 v[18:19], v[38:39], 1, v[18:19]
	s_waitcnt lgkmcnt(0)
	v_cvt_pk_bf16_f32 v0, v0, v2
	v_add_co_u32_e32 v2, vcc, 0x271c0000, v18
	s_nop 1
	v_addc_co_u32_e32 v3, vcc, 0, v19, vcc
	ds_write_b32 v208, v0 offset:192
.LBB0_708:
	s_or_b64 exec, exec, s[0:1]
	s_mov_b64 s[0:1], 0x1200
	s_waitcnt lgkmcnt(0)
	v_lshl_add_u64 v[2:3], v[82:83], 0, s[0:1]
	flat_load_ushort v0, v[2:3] offset:64
	s_nop 0
	flat_load_dword v2, v[72:73] offset:8
	s_waitcnt vmcnt(0) lgkmcnt(0)
	v_lshlrev_b32_e32 v0, 16, v0
	v_mul_f32_e32 v3, 0x3d372713, v0
	v_mul_f32_e32 v3, v3, v0
	v_fma_f32 v3, v3, v0, v0
	v_mul_f32_e32 v3, 0x3f4c422a, v3
	v_mul_f32_e32 v3, 0xc038aa3b, v3
	v_exp_f32_e32 v3, v3
	v_add_f32_e32 v2, v4, v2
	v_add_f32_e32 v3, 1.0, v3
	v_rcp_f32_e32 v3, v3
	s_nop 0
	v_mul_f32_e32 v0, v3, v0
	v_mul_f32_e32 v0, v2, v0
	ds_bpermute_b32 v2, v43, v0
	s_and_saveexec_b64 s[0:1], s[4:5]
	s_cbranch_execz .LBB0_710
	v_lshl_add_u64 v[18:19], v[84:85], 0, s[86:87]
	v_lshl_add_u64 v[18:19], v[38:39], 1, v[18:19]
	s_waitcnt lgkmcnt(0)
	v_cvt_pk_bf16_f32 v0, v0, v2
	v_add_co_u32_e32 v2, vcc, 0x271c0000, v18
	s_nop 1
	v_addc_co_u32_e32 v3, vcc, 0, v19, vcc
	ds_write_b32 v208, v0 offset:320
.LBB0_710:
	s_or_b64 exec, exec, s[0:1]
	s_mov_b64 s[0:1], 0x1200
	s_waitcnt lgkmcnt(0)
	v_lshl_add_u64 v[2:3], v[86:87], 0, s[0:1]
	flat_load_ushort v0, v[2:3] offset:64
	s_nop 0
	flat_load_dword v2, v[72:73] offset:12
	s_waitcnt vmcnt(0) lgkmcnt(0)
	v_lshlrev_b32_e32 v0, 16, v0
	v_mul_f32_e32 v3, 0x3d372713, v0
	v_mul_f32_e32 v3, v3, v0
	v_fma_f32 v3, v3, v0, v0
	v_mul_f32_e32 v3, 0x3f4c422a, v3
	v_mul_f32_e32 v3, 0xc038aa3b, v3
	v_exp_f32_e32 v3, v3
	v_add_f32_e32 v2, v5, v2
	v_add_f32_e32 v3, 1.0, v3
	v_rcp_f32_e32 v3, v3
	s_nop 0
	v_mul_f32_e32 v0, v3, v0
	v_mul_f32_e32 v0, v2, v0
	ds_bpermute_b32 v2, v43, v0
	s_and_saveexec_b64 s[0:1], s[4:5]
	s_cbranch_execz .LBB0_712
	v_lshl_add_u64 v[4:5], v[20:21], 0, s[86:87]
	v_lshl_add_u64 v[4:5], v[38:39], 1, v[4:5]
	s_waitcnt lgkmcnt(0)
	v_cvt_pk_bf16_f32 v0, v0, v2
	v_add_co_u32_e32 v2, vcc, 0x271c0000, v4
	s_nop 1
	v_addc_co_u32_e32 v3, vcc, 0, v5, vcc
	ds_write_b32 v208, v0 offset:448
; __device__ __forceinline__ float bf2f(unsigned short h) { return __uint_as_float(((unsigned)h) << 16); }
; __device__ __forceinline__ unsigned cvtpk(float lo, float hi) { unsigned r; asm volatile("v_cvt_pk_bf16_f32 %0, %1, %2" : "=v"(r) : "v"(lo), "v"(hi)); return r; }
; __device__ __forceinline__ int crow(int r, int hi) { return (r & 3) + 8 * (r >> 2) + 4 * hi; }
; __device__ __forceinline__ void ph_misc(const Args& a, char* lds, int l) {
;     ...
;         for (int ci = 0; ci < 2; ++ci)
; #pragma unroll
;             for (int r = 0; r < 16; ++r) { const int t = 32 * tb + crow(r, hi), c = 32 * (cb0 + ci) + r32; const size_t row = row0 + t;
;                 const float uval = gelu_tanh(bf2f(P[row * NIN + PC_U + g * 128 + c])); const float val = uval * (acc[ci][r] + b_s[l * 512 + g * 128 + t]);
;                 const float vn = __shfl_xor(val, 1); if ((r32 & 1) == 0) *(unsigned*)(MIX + row * DM + 1024 + g * 128 + c) = cvtpk(val, vn); }
.LBB0_712:
	s_or_b64 exec, exec, s[0:1]
	s_mov_b64 s[0:1], 0x1200
	s_waitcnt lgkmcnt(0)
	v_lshl_add_u64 v[2:3], v[88:89], 0, s[0:1]
	flat_load_ushort v0, v[2:3] offset:64
	s_nop 0
	flat_load_dword v2, v[72:73] offset:32
	s_waitcnt vmcnt(0) lgkmcnt(0)
	v_lshlrev_b32_e32 v0, 16, v0
	v_mul_f32_e32 v3, 0x3d372713, v0
	v_mul_f32_e32 v3, v3, v0
	v_fma_f32 v3, v3, v0, v0
	v_mul_f32_e32 v3, 0x3f4c422a, v3
	v_mul_f32_e32 v3, 0xc038aa3b, v3
	v_exp_f32_e32 v3, v3
	v_add_f32_e32 v2, v6, v2
	v_add_f32_e32 v3, 1.0, v3
	v_rcp_f32_e32 v3, v3
	s_nop 0
	v_mul_f32_e32 v0, v3, v0
	v_mul_f32_e32 v0, v2, v0
	ds_bpermute_b32 v2, v43, v0
	s_and_saveexec_b64 s[0:1], s[4:5]
	s_cbranch_execz .LBB0_714
	v_lshl_add_u64 v[4:5], v[90:91], 0, s[86:87]
	v_lshl_add_u64 v[4:5], v[38:39], 1, v[4:5]
	s_waitcnt lgkmcnt(0)
	v_cvt_pk_bf16_f32 v0, v0, v2
	v_add_co_u32_e32 v2, vcc, 0x271c0000, v4
	s_nop 1
	v_addc_co_u32_e32 v3, vcc, 0, v5, vcc
	ds_write_b32 v208, v0 offset:1088
.LBB0_714:
	s_or_b64 exec, exec, s[0:1]
	s_mov_b64 s[0:1], 0x1200
	s_waitcnt lgkmcnt(0)
	v_lshl_add_u64 v[2:3], v[92:93], 0, s[0:1]
	flat_load_ushort v0, v[2:3] offset:64
	s_nop 0
	flat_load_dword v2, v[72:73] offset:36
	s_waitcnt vmcnt(0) lgkmcnt(0)
	v_lshlrev_b32_e32 v0, 16, v0
	v_mul_f32_e32 v3, 0x3d372713, v0
	v_mul_f32_e32 v3, v3, v0
	v_fma_f32 v3, v3, v0, v0
	v_mul_f32_e32 v3, 0x3f4c422a, v3
	v_mul_f32_e32 v3, 0xc038aa3b, v3
	v_exp_f32_e32 v3, v3
	v_add_f32_e32 v2, v7, v2
	v_add_f32_e32 v3, 1.0, v3
	v_rcp_f32_e32 v3, v3
	s_nop 0
	v_mul_f32_e32 v0, v3, v0
	v_mul_f32_e32 v0, v2, v0
	ds_bpermute_b32 v2, v43, v0
	s_and_saveexec_b64 s[0:1], s[4:5]
	s_cbranch_execz .LBB0_716
	v_lshl_add_u64 v[4:5], v[22:23], 0, s[86:87]
	v_lshl_add_u64 v[4:5], v[38:39], 1, v[4:5]
	s_waitcnt lgkmcnt(0)
	v_cvt_pk_bf16_f32 v0, v0, v2
	v_add_co_u32_e32 v2, vcc, 0x271c0000, v4
	s_nop 1
	v_addc_co_u32_e32 v3, vcc, 0, v5, vcc
	ds_write_b32 v208, v0 offset:1216
.LBB0_716:
	s_or_b64 exec, exec, s[0:1]
	s_mov_b64 s[0:1], 0x1200
	s_waitcnt lgkmcnt(0)
	v_lshl_add_u64 v[2:3], v[94:95], 0, s[0:1]
	flat_load_ushort v0, v[2:3] offset:64
	s_nop 0
	flat_load_dword v2, v[72:73] offset:40
	s_waitcnt vmcnt(0) lgkmcnt(0)
	v_lshlrev_b32_e32 v0, 16, v0
	v_mul_f32_e32 v3, 0x3d372713, v0
	v_mul_f32_e32 v3, v3, v0
	v_fma_f32 v3, v3, v0, v0
	v_mul_f32_e32 v3, 0x3f4c422a, v3
	v_mul_f32_e32 v3, 0xc038aa3b, v3
	v_exp_f32_e32 v3, v3
	v_add_f32_e32 v2, v8, v2
	v_add_f32_e32 v3, 1.0, v3
	v_rcp_f32_e32 v3, v3
	s_nop 0
	v_mul_f32_e32 v0, v3, v0
	v_mul_f32_e32 v0, v2, v0
	ds_bpermute_b32 v2, v43, v0
	s_and_saveexec_b64 s[0:1], s[4:5]
	s_cbranch_execz .LBB0_718
	v_lshl_add_u64 v[4:5], v[96:97], 0, s[86:87]
	v_lshl_add_u64 v[4:5], v[38:39], 1, v[4:5]
	s_waitcnt lgkmcnt(0)
	v_cvt_pk_bf16_f32 v0, v0, v2
	v_add_co_u32_e32 v2, vcc, 0x271c0000, v4
	s_nop 1
	v_addc_co_u32_e32 v3, vcc, 0, v5, vcc
	ds_write_b32 v208, v0 offset:1344
.LBB0_718:
	s_or_b64 exec, exec, s[0:1]
	s_mov_b64 s[0:1], 0x1200
	s_waitcnt lgkmcnt(0)
	v_lshl_add_u64 v[2:3], v[98:99], 0, s[0:1]
	flat_load_ushort v0, v[2:3] offset:64
	s_nop 0
	flat_load_dword v2, v[72:73] offset:44
	s_waitcnt vmcnt(0) lgkmcnt(0)
	v_lshlrev_b32_e32 v0, 16, v0
	v_mul_f32_e32 v3, 0x3d372713, v0
	v_mul_f32_e32 v3, v3, v0
	v_fma_f32 v3, v3, v0, v0
	v_mul_f32_e32 v3, 0x3f4c422a, v3
	v_mul_f32_e32 v3, 0xc038aa3b, v3
	v_exp_f32_e32 v3, v3
	v_add_f32_e32 v2, v9, v2
	v_add_f32_e32 v3, 1.0, v3
	v_rcp_f32_e32 v3, v3
	s_nop 0
	v_mul_f32_e32 v0, v3, v0
	v_mul_f32_e32 v0, v2, v0
	ds_bpermute_b32 v2, v43, v0
	s_and_saveexec_b64 s[0:1], s[4:5]
	s_cbranch_execz .LBB0_720
	v_lshl_add_u64 v[4:5], v[24:25], 0, s[86:87]
	v_lshl_add_u64 v[4:5], v[38:39], 1, v[4:5]
	s_waitcnt lgkmcnt(0)
	v_cvt_pk_bf16_f32 v0, v0, v2
	v_add_co_u32_e32 v2, vcc, 0x271c0000, v4
	s_nop 1
	v_addc_co_u32_e32 v3, vcc, 0, v5, vcc
	ds_write_b32 v208, v0 offset:1472
.LBB0_720:
	s_or_b64 exec, exec, s[0:1]
	s_mov_b64 s[0:1], 0x1200
	s_waitcnt lgkmcnt(0)
	v_lshl_add_u64 v[2:3], v[100:101], 0, s[0:1]
	flat_load_ushort v0, v[2:3] offset:64
	s_nop 0
	flat_load_dword v2, v[72:73] offset:64
	s_waitcnt vmcnt(0) lgkmcnt(0)
	v_lshlrev_b32_e32 v0, 16, v0
	v_mul_f32_e32 v3, 0x3d372713, v0
	v_mul_f32_e32 v3, v3, v0
	v_fma_f32 v3, v3, v0, v0
	v_mul_f32_e32 v3, 0x3f4c422a, v3
	v_mul_f32_e32 v3, 0xc038aa3b, v3
	v_exp_f32_e32 v3, v3
	v_add_f32_e32 v2, v10, v2
	v_add_f32_e32 v3, 1.0, v3
	v_rcp_f32_e32 v3, v3
	s_nop 0
	v_mul_f32_e32 v0, v3, v0
	v_mul_f32_e32 v0, v2, v0
	ds_bpermute_b32 v2, v43, v0
	s_and_saveexec_b64 s[0:1], s[4:5]
	s_cbranch_execz .LBB0_722
	v_lshl_add_u64 v[4:5], v[102:103], 0, s[86:87]
	v_lshl_add_u64 v[4:5], v[38:39], 1, v[4:5]
	s_waitcnt lgkmcnt(0)
	v_cvt_pk_bf16_f32 v0, v0, v2
	v_add_co_u32_e32 v2, vcc, 0x271c0000, v4
	s_nop 1
	v_addc_co_u32_e32 v3, vcc, 0, v5, vcc
	ds_write_b32 v208, v0 offset:2112
.LBB0_722:
	s_or_b64 exec, exec, s[0:1]
	s_mov_b64 s[0:1], 0x1200
	s_waitcnt lgkmcnt(0)
	v_lshl_add_u64 v[2:3], v[104:105], 0, s[0:1]
	flat_load_ushort v0, v[2:3] offset:64
	s_nop 0
	flat_load_dword v2, v[72:73] offset:68
	s_waitcnt vmcnt(0) lgkmcnt(0)
	v_lshlrev_b32_e32 v0, 16, v0
	v_mul_f32_e32 v3, 0x3d372713, v0
	v_mul_f32_e32 v3, v3, v0
	v_fma_f32 v3, v3, v0, v0
	v_mul_f32_e32 v3, 0x3f4c422a, v3
	v_mul_f32_e32 v3, 0xc038aa3b, v3
	v_exp_f32_e32 v3, v3
	v_add_f32_e32 v2, v11, v2
	v_add_f32_e32 v3, 1.0, v3
	v_rcp_f32_e32 v3, v3
	s_nop 0
	v_mul_f32_e32 v0, v3, v0
	v_mul_f32_e32 v0, v2, v0
	ds_bpermute_b32 v2, v43, v0
	s_and_saveexec_b64 s[0:1], s[4:5]
	s_cbranch_execz .LBB0_724
	v_lshl_add_u64 v[4:5], v[26:27], 0, s[86:87]
	v_lshl_add_u64 v[4:5], v[38:39], 1, v[4:5]
	s_waitcnt lgkmcnt(0)
	v_cvt_pk_bf16_f32 v0, v0, v2
	v_add_co_u32_e32 v2, vcc, 0x271c0000, v4
	s_nop 1
	v_addc_co_u32_e32 v3, vcc, 0, v5, vcc
	ds_write_b32 v208, v0 offset:2240
; __device__ __forceinline__ float bf2f(unsigned short h) { return __uint_as_float(((unsigned)h) << 16); }
; __device__ __forceinline__ unsigned cvtpk(float lo, float hi) { unsigned r; asm volatile("v_cvt_pk_bf16_f32 %0, %1, %2" : "=v"(r) : "v"(lo), "v"(hi)); return r; }
; __device__ __forceinline__ int crow(int r, int hi) { return (r & 3) + 8 * (r >> 2) + 4 * hi; }
; __device__ __forceinline__ void ph_misc(const Args& a, char* lds, int l) {
;     ...
;         for (int ci = 0; ci < 2; ++ci)
; #pragma unroll
;             for (int r = 0; r < 16; ++r) { const int t = 32 * tb + crow(r, hi), c = 32 * (cb0 + ci) + r32; const size_t row = row0 + t;
;                 const float uval = gelu_tanh(bf2f(P[row * NIN + PC_U + g * 128 + c])); const float val = uval * (acc[ci][r] + b_s[l * 512 + g * 128 + t]);
;                 const float vn = __shfl_xor(val, 1); if ((r32 & 1) == 0) *(unsigned*)(MIX + row * DM + 1024 + g * 128 + c) = cvtpk(val, vn); }
.LBB0_724:
	s_or_b64 exec, exec, s[0:1]
	s_mov_b64 s[0:1], 0x1200
	s_waitcnt lgkmcnt(0)
	v_lshl_add_u64 v[2:3], v[106:107], 0, s[0:1]
	flat_load_ushort v0, v[2:3] offset:64
	s_nop 0
	flat_load_dword v2, v[72:73] offset:72
	s_waitcnt vmcnt(0) lgkmcnt(0)
	v_lshlrev_b32_e32 v0, 16, v0
	v_mul_f32_e32 v3, 0x3d372713, v0
	v_mul_f32_e32 v3, v3, v0
	v_fma_f32 v3, v3, v0, v0
	v_mul_f32_e32 v3, 0x3f4c422a, v3
	v_mul_f32_e32 v3, 0xc038aa3b, v3
	v_exp_f32_e32 v3, v3
	v_add_f32_e32 v2, v12, v2
	v_add_f32_e32 v3, 1.0, v3
	v_rcp_f32_e32 v3, v3
	s_nop 0
	v_mul_f32_e32 v0, v3, v0
	v_mul_f32_e32 v0, v2, v0
	ds_bpermute_b32 v2, v43, v0
	s_and_saveexec_b64 s[0:1], s[4:5]
	s_cbranch_execz .LBB0_726
	v_lshl_add_u64 v[4:5], v[108:109], 0, s[86:87]
	v_lshl_add_u64 v[4:5], v[38:39], 1, v[4:5]
	s_waitcnt lgkmcnt(0)
	v_cvt_pk_bf16_f32 v0, v0, v2
	v_add_co_u32_e32 v2, vcc, 0x271c0000, v4
	s_nop 1
	v_addc_co_u32_e32 v3, vcc, 0, v5, vcc
	ds_write_b32 v208, v0 offset:2368
.LBB0_726:
	s_or_b64 exec, exec, s[0:1]
	s_mov_b64 s[0:1], 0x1200
	s_waitcnt lgkmcnt(0)
	v_lshl_add_u64 v[2:3], v[110:111], 0, s[0:1]
	flat_load_ushort v0, v[2:3] offset:64
	s_nop 0
	flat_load_dword v2, v[72:73] offset:76
	s_waitcnt vmcnt(0) lgkmcnt(0)
	v_lshlrev_b32_e32 v0, 16, v0
	v_mul_f32_e32 v3, 0x3d372713, v0
	v_mul_f32_e32 v3, v3, v0
	v_fma_f32 v3, v3, v0, v0
	v_mul_f32_e32 v3, 0x3f4c422a, v3
	v_mul_f32_e32 v3, 0xc038aa3b, v3
	v_exp_f32_e32 v3, v3
	v_add_f32_e32 v2, v13, v2
	v_add_f32_e32 v3, 1.0, v3
	v_rcp_f32_e32 v3, v3
	s_nop 0
	v_mul_f32_e32 v0, v3, v0
	v_mul_f32_e32 v0, v2, v0
	ds_bpermute_b32 v2, v43, v0
	s_and_saveexec_b64 s[0:1], s[4:5]
	s_cbranch_execz .LBB0_728
	v_lshl_add_u64 v[4:5], v[28:29], 0, s[86:87]
	v_lshl_add_u64 v[4:5], v[38:39], 1, v[4:5]
	s_waitcnt lgkmcnt(0)
	v_cvt_pk_bf16_f32 v0, v0, v2
	v_add_co_u32_e32 v2, vcc, 0x271c0000, v4
	s_nop 1
	v_addc_co_u32_e32 v3, vcc, 0, v5, vcc
	ds_write_b32 v208, v0 offset:2496
.LBB0_728:
	s_or_b64 exec, exec, s[0:1]
	s_mov_b64 s[0:1], 0x1200
	s_waitcnt lgkmcnt(0)
	v_lshl_add_u64 v[2:3], v[112:113], 0, s[0:1]
	flat_load_ushort v0, v[2:3] offset:64
	s_nop 0
	flat_load_dword v2, v[72:73] offset:96
	s_waitcnt vmcnt(0) lgkmcnt(0)
	v_lshlrev_b32_e32 v0, 16, v0
	v_mul_f32_e32 v3, 0x3d372713, v0
	v_mul_f32_e32 v3, v3, v0
	v_fma_f32 v3, v3, v0, v0
	v_mul_f32_e32 v3, 0x3f4c422a, v3
	v_mul_f32_e32 v3, 0xc038aa3b, v3
	v_exp_f32_e32 v3, v3
	v_add_f32_e32 v2, v14, v2
	v_add_f32_e32 v3, 1.0, v3
	v_rcp_f32_e32 v3, v3
	s_nop 0
	v_mul_f32_e32 v0, v3, v0
	v_mul_f32_e32 v0, v2, v0
	ds_bpermute_b32 v2, v43, v0
	s_and_saveexec_b64 s[0:1], s[4:5]
	s_cbranch_execz .LBB0_730
	v_lshl_add_u64 v[4:5], v[114:115], 0, s[86:87]
	v_lshl_add_u64 v[4:5], v[38:39], 1, v[4:5]
	s_waitcnt lgkmcnt(0)
	v_cvt_pk_bf16_f32 v0, v0, v2
	v_add_co_u32_e32 v2, vcc, 0x271c0000, v4
	s_nop 1
	v_addc_co_u32_e32 v3, vcc, 0, v5, vcc
	ds_write_b32 v208, v0 offset:3136
.LBB0_730:
	s_or_b64 exec, exec, s[0:1]
	s_mov_b64 s[0:1], 0x1200
	s_waitcnt lgkmcnt(0)
	v_lshl_add_u64 v[2:3], v[116:117], 0, s[0:1]
	flat_load_ushort v0, v[2:3] offset:64
	s_nop 0
	flat_load_dword v2, v[72:73] offset:100
	s_waitcnt vmcnt(0) lgkmcnt(0)
	v_lshlrev_b32_e32 v0, 16, v0
	v_mul_f32_e32 v3, 0x3d372713, v0
	v_mul_f32_e32 v3, v3, v0
	v_fma_f32 v3, v3, v0, v0
	v_mul_f32_e32 v3, 0x3f4c422a, v3
	v_mul_f32_e32 v3, 0xc038aa3b, v3
	v_exp_f32_e32 v3, v3
	v_add_f32_e32 v2, v15, v2
	v_add_f32_e32 v3, 1.0, v3
	v_rcp_f32_e32 v3, v3
	s_nop 0
	v_mul_f32_e32 v0, v3, v0
	v_mul_f32_e32 v0, v2, v0
	ds_bpermute_b32 v2, v43, v0
	s_and_saveexec_b64 s[0:1], s[4:5]
	s_cbranch_execz .LBB0_732
	v_lshl_add_u64 v[4:5], v[30:31], 0, s[86:87]
	v_lshl_add_u64 v[4:5], v[38:39], 1, v[4:5]
	s_waitcnt lgkmcnt(0)
	v_cvt_pk_bf16_f32 v0, v0, v2
	v_add_co_u32_e32 v2, vcc, 0x271c0000, v4
	s_nop 1
	v_addc_co_u32_e32 v3, vcc, 0, v5, vcc
	ds_write_b32 v208, v0 offset:3264
.LBB0_732:
	s_or_b64 exec, exec, s[0:1]
	s_mov_b64 s[0:1], 0x1200
	s_waitcnt lgkmcnt(0)
	v_lshl_add_u64 v[2:3], v[118:119], 0, s[0:1]
	flat_load_ushort v0, v[2:3] offset:64
	s_nop 0
	flat_load_dword v2, v[72:73] offset:104
	s_waitcnt vmcnt(0) lgkmcnt(0)
	v_lshlrev_b32_e32 v0, 16, v0
	v_mul_f32_e32 v3, 0x3d372713, v0
	v_mul_f32_e32 v3, v3, v0
	v_fma_f32 v3, v3, v0, v0
	v_mul_f32_e32 v3, 0x3f4c422a, v3
	v_mul_f32_e32 v3, 0xc038aa3b, v3
	v_exp_f32_e32 v3, v3
	v_add_f32_e32 v2, v16, v2
	v_add_f32_e32 v3, 1.0, v3
	v_rcp_f32_e32 v3, v3
	s_nop 0
	v_mul_f32_e32 v0, v3, v0
	v_mul_f32_e32 v0, v2, v0
	ds_bpermute_b32 v2, v43, v0
	s_and_saveexec_b64 s[0:1], s[4:5]
	s_cbranch_execz .LBB0_734
	v_lshl_add_u64 v[4:5], v[120:121], 0, s[86:87]
	v_lshl_add_u64 v[4:5], v[38:39], 1, v[4:5]
	s_waitcnt lgkmcnt(0)
	v_cvt_pk_bf16_f32 v0, v0, v2
	v_add_co_u32_e32 v2, vcc, 0x271c0000, v4
	s_nop 1
	v_addc_co_u32_e32 v3, vcc, 0, v5, vcc
	ds_write_b32 v208, v0 offset:3392
.LBB0_734:
	s_or_b64 exec, exec, s[0:1]
	s_mov_b64 s[0:1], 0x1200
	s_waitcnt lgkmcnt(0)
	v_lshl_add_u64 v[2:3], v[122:123], 0, s[0:1]
	flat_load_ushort v0, v[2:3] offset:64
	s_nop 0
	flat_load_dword v2, v[72:73] offset:108
	s_waitcnt vmcnt(0) lgkmcnt(0)
	v_lshlrev_b32_e32 v0, 16, v0
	v_mul_f32_e32 v3, 0x3d372713, v0
	v_mul_f32_e32 v3, v3, v0
	v_fma_f32 v3, v3, v0, v0
	v_mul_f32_e32 v3, 0x3f4c422a, v3
	v_mul_f32_e32 v3, 0xc038aa3b, v3
	v_exp_f32_e32 v3, v3
	v_add_f32_e32 v2, v17, v2
	v_add_f32_e32 v3, 1.0, v3
	v_rcp_f32_e32 v3, v3
	s_nop 0
	v_mul_f32_e32 v0, v3, v0
	v_mul_f32_e32 v0, v2, v0
	ds_bpermute_b32 v2, v43, v0
	s_and_saveexec_b64 s[0:1], s[4:5]
	s_cbranch_execz .LBB0_659
	v_lshl_add_u64 v[4:5], v[32:33], 0, s[86:87]
	v_lshl_add_u64 v[4:5], v[38:39], 1, v[4:5]
	s_waitcnt lgkmcnt(0)
	v_cvt_pk_bf16_f32 v0, v0, v2
	v_add_co_u32_e32 v2, vcc, 0x271c0000, v4
	s_nop 1
	v_addc_co_u32_e32 v3, vcc, 0, v5, vcc
	ds_write_b32 v208, v0 offset:3520
	s_branch .LBB0_659
